# GEMM K-loops: LDS-DMA loads use SGPR base + 32-bit VGPR offset (16 VALU 64-bit address adds per iteration removed from the loader segments)
# speedup vs baseline: 1.0063x; 1.0063x over previous
.Lsp_205:
.LBB0_205:
	s_add_u32 s16, s42, 0xfff80080
	s_addc_u32 s17, s43, -1
	s_add_i32 s89, 0, 0x10000
	s_cmp_eq_u32 s88, 28
	s_cselect_b32 s45, s27, s17
	s_cselect_b32 s44, s73, s16
	s_cselect_b32 s29, s23, s78
	s_cselect_b32 s28, s74, s77
	s_add_i32 s91, 0, 0x14000
	v_add_u32_e32 v144, s89, v227
	v_add_u32_e32 v170, s91, v227
	ds_read_b128 v[132:135], v144
	ds_read_b128 v[136:139], v144 offset:1024
	ds_read_b128 v[140:143], v144 offset:2048
	ds_read_b128 v[144:147], v144 offset:3072
	ds_read_b128 v[148:151], v170
	ds_read_b128 v[152:155], v170 offset:1024
	ds_read_b128 v[166:169], v170 offset:2048
	ds_read_b128 v[170:173], v170 offset:3072
	s_add_i32 m0, s31, 0xc000
	ds_read_b128 v[184:187], v229
	ds_read_b128 v[188:191], v229 offset:1024
	ds_read_b128 v[192:195], v229 offset:2048
	ds_read_b128 v[196:199], v229 offset:3072
	ds_read_b128 v[200:203], v229 offset:4096
	ds_read_b128 v[204:207], v229 offset:5120
	ds_read_b128 v[208:211], v229 offset:6144
	ds_read_b128 v[212:215], v229 offset:7168
	global_load_lds_dwordx4 v162, s[42:43]
	s_add_i32 m0, s31, 0xe000
	s_nop 0
	global_load_lds_dwordx4 v164, s[42:43]
	s_waitcnt vmcnt(8)
	s_waitcnt lgkmcnt(0)

	s_barrier
	v_mfma_f32_16x16x32_bf16 v[128:131], v[132:135], v[184:187], v[128:131]
	v_mfma_f32_16x16x32_bf16 v[124:127], v[140:143], v[184:187], v[124:127]
	v_mfma_f32_16x16x32_bf16 v[112:115], v[132:135], v[192:195], v[112:115]
	v_mfma_f32_16x16x32_bf16 v[108:111], v[140:143], v[192:195], v[108:111]
	v_mfma_f32_16x16x32_bf16 v[96:99], v[132:135], v[200:203], v[96:99]
	v_mfma_f32_16x16x32_bf16 v[92:95], v[140:143], v[200:203], v[92:95]
	v_mfma_f32_16x16x32_bf16 v[80:83], v[132:135], v[208:211], v[80:83]
	v_mfma_f32_16x16x32_bf16 v[76:79], v[140:143], v[208:211], v[76:79]
	v_mfma_f32_16x16x32_bf16 v[128:131], v[136:139], v[188:191], v[128:131]
	v_mfma_f32_16x16x32_bf16 v[124:127], v[144:147], v[188:191], v[124:127]
	v_mfma_f32_16x16x32_bf16 v[112:115], v[136:139], v[196:199], v[112:115]
	v_mfma_f32_16x16x32_bf16 v[108:111], v[144:147], v[196:199], v[108:111]
	v_mfma_f32_16x16x32_bf16 v[96:99], v[136:139], v[204:207], v[96:99]
	v_mfma_f32_16x16x32_bf16 v[92:95], v[144:147], v[204:207], v[92:95]
	v_mfma_f32_16x16x32_bf16 v[80:83], v[136:139], v[212:215], v[80:83]
	v_mfma_f32_16x16x32_bf16 v[76:79], v[144:147], v[212:215], v[76:79]
	v_mfma_f32_16x16x32_bf16 v[120:123], v[148:151], v[184:187], v[120:123]
	v_mfma_f32_16x16x32_bf16 v[116:119], v[166:169], v[184:187], v[116:119]
	v_mfma_f32_16x16x32_bf16 v[104:107], v[148:151], v[192:195], v[104:107]
	v_mfma_f32_16x16x32_bf16 v[100:103], v[166:169], v[192:195], v[100:103]
	v_mfma_f32_16x16x32_bf16 v[88:91], v[148:151], v[200:203], v[88:91]
	v_mfma_f32_16x16x32_bf16 v[84:87], v[166:169], v[200:203], v[84:87]
	v_mfma_f32_16x16x32_bf16 v[72:75], v[148:151], v[208:211], v[72:75]
	v_mfma_f32_16x16x32_bf16 v[68:71], v[166:169], v[208:211], v[68:71]
	v_mfma_f32_16x16x32_bf16 v[120:123], v[152:155], v[188:191], v[120:123]
	v_mfma_f32_16x16x32_bf16 v[116:119], v[170:173], v[188:191], v[116:119]
	v_mfma_f32_16x16x32_bf16 v[104:107], v[152:155], v[196:199], v[104:107]
	v_mfma_f32_16x16x32_bf16 v[100:103], v[170:173], v[196:199], v[100:103]
	v_mfma_f32_16x16x32_bf16 v[88:91], v[152:155], v[204:207], v[88:91]
	v_mfma_f32_16x16x32_bf16 v[84:87], v[170:173], v[204:207], v[84:87]
	v_mfma_f32_16x16x32_bf16 v[72:75], v[152:155], v[212:215], v[72:75]
	v_mfma_f32_16x16x32_bf16 v[68:71], v[170:173], v[212:215], v[68:71]
	s_barrier

	s_add_i32 s16, s89, s3
	s_mov_b32 m0, s16
	ds_read_b128 v[184:187], v229 offset:16384
	ds_read_b128 v[188:191], v229 offset:17408
	ds_read_b128 v[192:195], v229 offset:18432
	ds_read_b128 v[196:199], v229 offset:19456
	ds_read_b128 v[200:203], v229 offset:20480
	ds_read_b128 v[204:207], v229 offset:21504
	ds_read_b128 v[208:211], v229 offset:22528
	ds_read_b128 v[212:215], v229 offset:23552
	global_load_lds_dwordx4 v2, s[28:29]
	s_add_i32 m0, s16, 0x2000
	s_add_u32 s16, s28, 0x80000
	s_addc_u32 s17, s29, 0
	s_add_i32 s89, s91, s3
	global_load_lds_dwordx4 v156, s[28:29]
	s_mov_b32 m0, s89
	s_nop 0
	global_load_lds_dwordx4 v2, s[16:17]
	s_add_i32 m0, s89, 0x2000
	s_nop 0
	global_load_lds_dwordx4 v156, s[16:17]
	s_mov_b32 m0, s31
	s_nop 0
	global_load_lds_dwordx4 v160, s[44:45]
	s_mov_b32 m0, s33
	s_nop 0
	global_load_lds_dwordx4 v158, s[44:45]
	s_waitcnt vmcnt(8)
	s_waitcnt lgkmcnt(0)

	s_barrier
	v_mfma_f32_16x16x32_bf16 v[64:67], v[132:135], v[184:187], v[64:67]
	v_mfma_f32_16x16x32_bf16 v[60:63], v[140:143], v[184:187], v[60:63]
	v_mfma_f32_16x16x32_bf16 v[48:51], v[132:135], v[192:195], v[48:51]
	v_mfma_f32_16x16x32_bf16 v[44:47], v[140:143], v[192:195], v[44:47]
	v_mfma_f32_16x16x32_bf16 v[32:35], v[132:135], v[200:203], v[32:35]
	v_mfma_f32_16x16x32_bf16 v[28:31], v[140:143], v[200:203], v[28:31]
	v_mfma_f32_16x16x32_bf16 v[16:19], v[132:135], v[208:211], v[16:19]
	v_mfma_f32_16x16x32_bf16 v[12:15], v[140:143], v[208:211], v[12:15]
	v_mfma_f32_16x16x32_bf16 v[64:67], v[136:139], v[188:191], v[64:67]
	v_mfma_f32_16x16x32_bf16 v[60:63], v[144:147], v[188:191], v[60:63]
	v_mfma_f32_16x16x32_bf16 v[48:51], v[136:139], v[196:199], v[48:51]
	v_mfma_f32_16x16x32_bf16 v[44:47], v[144:147], v[196:199], v[44:47]
	v_mfma_f32_16x16x32_bf16 v[32:35], v[136:139], v[204:207], v[32:35]
	v_mfma_f32_16x16x32_bf16 v[28:31], v[144:147], v[204:207], v[28:31]
	v_mfma_f32_16x16x32_bf16 v[16:19], v[136:139], v[212:215], v[16:19]
	v_mfma_f32_16x16x32_bf16 v[12:15], v[144:147], v[212:215], v[12:15]
	v_mfma_f32_16x16x32_bf16 v[56:59], v[148:151], v[184:187], v[56:59]
	v_mfma_f32_16x16x32_bf16 v[52:55], v[166:169], v[184:187], v[52:55]
	v_mfma_f32_16x16x32_bf16 v[40:43], v[148:151], v[192:195], v[40:43]
	v_mfma_f32_16x16x32_bf16 v[36:39], v[166:169], v[192:195], v[36:39]
	v_mfma_f32_16x16x32_bf16 v[24:27], v[148:151], v[200:203], v[24:27]
	v_mfma_f32_16x16x32_bf16 v[20:23], v[166:169], v[200:203], v[20:23]
	v_mfma_f32_16x16x32_bf16 v[8:11], v[148:151], v[208:211], v[8:11]
	v_mfma_f32_16x16x32_bf16 v[4:7], v[166:169], v[208:211], v[4:7]
	v_mfma_f32_16x16x32_bf16 v[56:59], v[152:155], v[188:191], v[56:59]
	v_mfma_f32_16x16x32_bf16 v[52:55], v[170:173], v[188:191], v[52:55]
	v_mfma_f32_16x16x32_bf16 v[40:43], v[152:155], v[196:199], v[40:43]
	v_mfma_f32_16x16x32_bf16 v[36:39], v[170:173], v[196:199], v[36:39]
	v_mfma_f32_16x16x32_bf16 v[24:27], v[152:155], v[204:207], v[24:27]
	v_mfma_f32_16x16x32_bf16 v[20:23], v[170:173], v[204:207], v[20:23]
	v_mfma_f32_16x16x32_bf16 v[8:11], v[152:155], v[212:215], v[8:11]
	v_mfma_f32_16x16x32_bf16 v[4:7], v[170:173], v[212:215], v[4:7]
	s_barrier

	s_add_i32 s89, 0, 0x18000
	s_add_i32 s91, 0, 0x1c000
	v_add_u32_e32 v144, s89, v227
	v_add_u32_e32 v170, s91, v227
	ds_read_b128 v[132:135], v144
	ds_read_b128 v[136:139], v144 offset:1024
	ds_read_b128 v[140:143], v144 offset:2048
	ds_read_b128 v[144:147], v144 offset:3072
	ds_read_b128 v[148:151], v170
	ds_read_b128 v[152:155], v170 offset:1024
	ds_read_b128 v[166:169], v170 offset:2048
	ds_read_b128 v[170:173], v170 offset:3072
	s_add_u32 s16, s44, 0x80000
	s_addc_u32 s17, s45, 0
	s_mov_b32 m0, s46
	ds_read_b128 v[184:187], v229 offset:32768
	ds_read_b128 v[188:191], v229 offset:33792
	ds_read_b128 v[192:195], v229 offset:34816
	ds_read_b128 v[196:199], v229 offset:35840
	ds_read_b128 v[200:203], v229 offset:36864
	ds_read_b128 v[204:207], v229 offset:37888
	ds_read_b128 v[208:211], v229 offset:38912
	ds_read_b128 v[212:215], v229 offset:39936
	global_load_lds_dwordx4 v160, s[16:17]
	s_mov_b32 m0, s47
	s_nop 0
	global_load_lds_dwordx4 v158, s[16:17]
	s_waitcnt vmcnt(8)
	s_waitcnt lgkmcnt(0)

	s_barrier
	v_mfma_f32_16x16x32_bf16 v[128:131], v[132:135], v[184:187], v[128:131]
	v_mfma_f32_16x16x32_bf16 v[124:127], v[140:143], v[184:187], v[124:127]
	v_mfma_f32_16x16x32_bf16 v[112:115], v[132:135], v[192:195], v[112:115]
	v_mfma_f32_16x16x32_bf16 v[108:111], v[140:143], v[192:195], v[108:111]
	v_mfma_f32_16x16x32_bf16 v[96:99], v[132:135], v[200:203], v[96:99]
	v_mfma_f32_16x16x32_bf16 v[92:95], v[140:143], v[200:203], v[92:95]
	v_mfma_f32_16x16x32_bf16 v[80:83], v[132:135], v[208:211], v[80:83]
	v_mfma_f32_16x16x32_bf16 v[76:79], v[140:143], v[208:211], v[76:79]
	v_mfma_f32_16x16x32_bf16 v[128:131], v[136:139], v[188:191], v[128:131]
	v_mfma_f32_16x16x32_bf16 v[124:127], v[144:147], v[188:191], v[124:127]
	v_mfma_f32_16x16x32_bf16 v[112:115], v[136:139], v[196:199], v[112:115]
	v_mfma_f32_16x16x32_bf16 v[108:111], v[144:147], v[196:199], v[108:111]
	v_mfma_f32_16x16x32_bf16 v[96:99], v[136:139], v[204:207], v[96:99]
	v_mfma_f32_16x16x32_bf16 v[92:95], v[144:147], v[204:207], v[92:95]
	v_mfma_f32_16x16x32_bf16 v[80:83], v[136:139], v[212:215], v[80:83]
	v_mfma_f32_16x16x32_bf16 v[76:79], v[144:147], v[212:215], v[76:79]
	v_mfma_f32_16x16x32_bf16 v[120:123], v[148:151], v[184:187], v[120:123]
	v_mfma_f32_16x16x32_bf16 v[116:119], v[166:169], v[184:187], v[116:119]
	v_mfma_f32_16x16x32_bf16 v[104:107], v[148:151], v[192:195], v[104:107]
	v_mfma_f32_16x16x32_bf16 v[100:103], v[166:169], v[192:195], v[100:103]
	v_mfma_f32_16x16x32_bf16 v[88:91], v[148:151], v[200:203], v[88:91]
	v_mfma_f32_16x16x32_bf16 v[84:87], v[166:169], v[200:203], v[84:87]
	v_mfma_f32_16x16x32_bf16 v[72:75], v[148:151], v[208:211], v[72:75]
	v_mfma_f32_16x16x32_bf16 v[68:71], v[166:169], v[208:211], v[68:71]
	v_mfma_f32_16x16x32_bf16 v[120:123], v[152:155], v[188:191], v[120:123]
	v_mfma_f32_16x16x32_bf16 v[116:119], v[170:173], v[188:191], v[116:119]
	v_mfma_f32_16x16x32_bf16 v[104:107], v[152:155], v[196:199], v[104:107]
	v_mfma_f32_16x16x32_bf16 v[100:103], v[170:173], v[196:199], v[100:103]
	v_mfma_f32_16x16x32_bf16 v[88:91], v[152:155], v[204:207], v[88:91]
	v_mfma_f32_16x16x32_bf16 v[84:87], v[170:173], v[204:207], v[84:87]
	v_mfma_f32_16x16x32_bf16 v[72:75], v[152:155], v[212:215], v[72:75]
	v_mfma_f32_16x16x32_bf16 v[68:71], v[170:173], v[212:215], v[68:71]
	s_barrier

	s_add_i32 s16, s89, s3
	s_mov_b32 m0, s16
	ds_read_b128 v[184:187], v229 offset:49152
	ds_read_b128 v[188:191], v229 offset:50176
	ds_read_b128 v[192:195], v229 offset:51200
	ds_read_b128 v[196:199], v229 offset:52224
	ds_read_b128 v[200:203], v229 offset:53248
	ds_read_b128 v[204:207], v229 offset:54272
	ds_read_b128 v[208:211], v229 offset:55296
	ds_read_b128 v[212:215], v229 offset:56320
	s_add_u32 s100, s28, s24
	s_addc_u32 s101, s29, s25
	global_load_lds_dwordx4 v2, s[100:101]
	s_add_i32 m0, s16, 0x2000
	s_add_u32 s16, s28, 0x80080
	s_addc_u32 s17, s29, 0
	s_add_i32 s28, s91, s3
	global_load_lds_dwordx4 v156, s[100:101]
	s_mov_b32 m0, s28
	s_nop 0
	global_load_lds_dwordx4 v2, s[16:17]
	s_add_i32 m0, s28, 0x2000
	s_nop 0
	global_load_lds_dwordx4 v156, s[16:17]
	s_mov_b32 m0, s48
	s_nop 0
	s_add_u32 s100, s44, s24
	s_addc_u32 s101, s45, s25
	global_load_lds_dwordx4 v160, s[100:101]
	s_mov_b32 m0, s49
	s_nop 0
	global_load_lds_dwordx4 v158, s[100:101]
	s_waitcnt vmcnt(8)
	s_waitcnt lgkmcnt(0)

	s_barrier
	v_mfma_f32_16x16x32_bf16 v[64:67], v[132:135], v[184:187], v[64:67]
	v_mfma_f32_16x16x32_bf16 v[60:63], v[140:143], v[184:187], v[60:63]
	v_mfma_f32_16x16x32_bf16 v[48:51], v[132:135], v[192:195], v[48:51]
	v_mfma_f32_16x16x32_bf16 v[44:47], v[140:143], v[192:195], v[44:47]
	v_mfma_f32_16x16x32_bf16 v[32:35], v[132:135], v[200:203], v[32:35]
	v_mfma_f32_16x16x32_bf16 v[28:31], v[140:143], v[200:203], v[28:31]
	v_mfma_f32_16x16x32_bf16 v[16:19], v[132:135], v[208:211], v[16:19]
	v_mfma_f32_16x16x32_bf16 v[12:15], v[140:143], v[208:211], v[12:15]
	v_mfma_f32_16x16x32_bf16 v[64:67], v[136:139], v[188:191], v[64:67]
	v_mfma_f32_16x16x32_bf16 v[60:63], v[144:147], v[188:191], v[60:63]
	v_mfma_f32_16x16x32_bf16 v[48:51], v[136:139], v[196:199], v[48:51]
	v_mfma_f32_16x16x32_bf16 v[44:47], v[144:147], v[196:199], v[44:47]
	v_mfma_f32_16x16x32_bf16 v[32:35], v[136:139], v[204:207], v[32:35]
	v_mfma_f32_16x16x32_bf16 v[28:31], v[144:147], v[204:207], v[28:31]
	v_mfma_f32_16x16x32_bf16 v[16:19], v[136:139], v[212:215], v[16:19]
	v_mfma_f32_16x16x32_bf16 v[12:15], v[144:147], v[212:215], v[12:15]
	v_mfma_f32_16x16x32_bf16 v[56:59], v[148:151], v[184:187], v[56:59]
	v_mfma_f32_16x16x32_bf16 v[52:55], v[166:169], v[184:187], v[52:55]
	v_mfma_f32_16x16x32_bf16 v[40:43], v[148:151], v[192:195], v[40:43]
	v_mfma_f32_16x16x32_bf16 v[36:39], v[166:169], v[192:195], v[36:39]
	v_mfma_f32_16x16x32_bf16 v[24:27], v[148:151], v[200:203], v[24:27]
	v_mfma_f32_16x16x32_bf16 v[20:23], v[166:169], v[200:203], v[20:23]
	v_mfma_f32_16x16x32_bf16 v[8:11], v[148:151], v[208:211], v[8:11]
	v_mfma_f32_16x16x32_bf16 v[4:7], v[166:169], v[208:211], v[4:7]
	v_mfma_f32_16x16x32_bf16 v[56:59], v[152:155], v[188:191], v[56:59]
	v_mfma_f32_16x16x32_bf16 v[52:55], v[170:173], v[188:191], v[52:55]
	v_mfma_f32_16x16x32_bf16 v[40:43], v[152:155], v[196:199], v[40:43]
	v_mfma_f32_16x16x32_bf16 v[36:39], v[170:173], v[196:199], v[36:39]
	v_mfma_f32_16x16x32_bf16 v[24:27], v[152:155], v[204:207], v[24:27]
	v_mfma_f32_16x16x32_bf16 v[20:23], v[170:173], v[204:207], v[20:23]
	v_mfma_f32_16x16x32_bf16 v[8:11], v[152:155], v[212:215], v[8:11]
	v_mfma_f32_16x16x32_bf16 v[4:7], v[170:173], v[212:215], v[4:7]
	s_barrier

	s_add_i32 s88, s88, 2
	s_add_u32 s42, s42, 0x100
	s_addc_u32 s43, s43, 0
	s_add_u32 s77, s77, 0x100
	s_addc_u32 s78, s78, 0
	s_cmp_gt_u32 s88, 29
	s_cbranch_scc0 .LBB0_205
	s_setprio 0
	v_mov_b32_e32 v176, 0xc2000000

.Lsp_366:
.LBB0_366:
	s_add_u32 s48, s50, 0x100
	s_addc_u32 s49, s51, 0
	s_add_i32 s16, 0, 0x10000
	s_cmpk_eq_i32 s22, 0x54
	s_cselect_b32 vcc_hi, s19, s49
	s_cselect_b32 vcc_lo, s18, s48
	s_cselect_b32 s29, s27, s33
	s_cselect_b32 s28, s26, s31
	s_add_i32 s23, 0, 0x14000
	v_add_u32_e32 v144, s16, v244
	v_add_u32_e32 v160, s23, v244
	ds_read_b128 v[132:135], v144
	ds_read_b128 v[136:139], v144 offset:1024
	ds_read_b128 v[140:143], v144 offset:2048
	ds_read_b128 v[144:147], v144 offset:3072
	ds_read_b128 v[148:151], v160
	ds_read_b128 v[152:155], v160 offset:1024
	ds_read_b128 v[156:159], v160 offset:2048
	ds_read_b128 v[160:163], v160 offset:3072
	s_add_i32 m0, s74, 0xc000
	ds_read_b128 v[164:167], v246
	ds_read_b128 v[188:191], v246 offset:1024
	ds_read_b128 v[192:195], v246 offset:2048
	ds_read_b128 v[196:199], v246 offset:3072
	ds_read_b128 v[200:203], v246 offset:4096
	ds_read_b128 v[204:207], v246 offset:5120
	ds_read_b128 v[208:211], v246 offset:6144
	ds_read_b128 v[212:215], v246 offset:7168
	global_load_lds_dwordx4 v184, s[50:51]
	s_add_i32 m0, s74, 0xe000
	s_nop 0
	global_load_lds_dwordx4 v186, s[50:51]
	s_waitcnt vmcnt(8)
	s_waitcnt lgkmcnt(0)

	s_barrier
	v_mfma_f32_16x16x32_bf16 v[128:131], v[132:135], v[164:167], v[128:131]
	v_mfma_f32_16x16x32_bf16 v[124:127], v[140:143], v[164:167], v[124:127]
	v_mfma_f32_16x16x32_bf16 v[112:115], v[132:135], v[192:195], v[112:115]
	v_mfma_f32_16x16x32_bf16 v[108:111], v[140:143], v[192:195], v[108:111]
	v_mfma_f32_16x16x32_bf16 v[96:99], v[132:135], v[200:203], v[96:99]
	v_mfma_f32_16x16x32_bf16 v[92:95], v[140:143], v[200:203], v[92:95]
	v_mfma_f32_16x16x32_bf16 v[80:83], v[132:135], v[208:211], v[80:83]
	v_mfma_f32_16x16x32_bf16 v[76:79], v[140:143], v[208:211], v[76:79]
	v_mfma_f32_16x16x32_bf16 v[128:131], v[136:139], v[188:191], v[128:131]
	v_mfma_f32_16x16x32_bf16 v[124:127], v[144:147], v[188:191], v[124:127]
	v_mfma_f32_16x16x32_bf16 v[112:115], v[136:139], v[196:199], v[112:115]
	v_mfma_f32_16x16x32_bf16 v[108:111], v[144:147], v[196:199], v[108:111]
	v_mfma_f32_16x16x32_bf16 v[96:99], v[136:139], v[204:207], v[96:99]
	v_mfma_f32_16x16x32_bf16 v[92:95], v[144:147], v[204:207], v[92:95]
	v_mfma_f32_16x16x32_bf16 v[80:83], v[136:139], v[212:215], v[80:83]
	v_mfma_f32_16x16x32_bf16 v[76:79], v[144:147], v[212:215], v[76:79]
	v_mfma_f32_16x16x32_bf16 v[120:123], v[148:151], v[164:167], v[120:123]
	v_mfma_f32_16x16x32_bf16 v[116:119], v[156:159], v[164:167], v[116:119]
	v_mfma_f32_16x16x32_bf16 v[104:107], v[148:151], v[192:195], v[104:107]
	v_mfma_f32_16x16x32_bf16 v[100:103], v[156:159], v[192:195], v[100:103]
	v_mfma_f32_16x16x32_bf16 v[88:91], v[148:151], v[200:203], v[88:91]
	v_mfma_f32_16x16x32_bf16 v[84:87], v[156:159], v[200:203], v[84:87]
	v_mfma_f32_16x16x32_bf16 v[72:75], v[148:151], v[208:211], v[72:75]
	v_mfma_f32_16x16x32_bf16 v[68:71], v[156:159], v[208:211], v[68:71]
	v_mfma_f32_16x16x32_bf16 v[120:123], v[152:155], v[188:191], v[120:123]
	v_mfma_f32_16x16x32_bf16 v[116:119], v[160:163], v[188:191], v[116:119]
	v_mfma_f32_16x16x32_bf16 v[104:107], v[152:155], v[196:199], v[104:107]
	v_mfma_f32_16x16x32_bf16 v[100:103], v[160:163], v[196:199], v[100:103]
	v_mfma_f32_16x16x32_bf16 v[88:91], v[152:155], v[204:207], v[88:91]
	v_mfma_f32_16x16x32_bf16 v[84:87], v[160:163], v[204:207], v[84:87]
	v_mfma_f32_16x16x32_bf16 v[72:75], v[152:155], v[212:215], v[72:75]
	v_mfma_f32_16x16x32_bf16 v[68:71], v[160:163], v[212:215], v[68:71]
	s_barrier

	s_add_i32 s16, s16, s73
	s_mov_b32 m0, s16
	ds_read_b128 v[164:167], v246 offset:16384
	ds_read_b128 v[188:191], v246 offset:17408
	ds_read_b128 v[192:195], v246 offset:18432
	ds_read_b128 v[196:199], v246 offset:19456
	ds_read_b128 v[200:203], v246 offset:20480
	ds_read_b128 v[204:207], v246 offset:21504
	ds_read_b128 v[208:211], v246 offset:22528
	ds_read_b128 v[212:215], v246 offset:23552
	global_load_lds_dwordx4 v2, s[28:29]
	s_add_i32 m0, s16, 0x2000
	s_add_u32 s16, s28, 0x58000
	s_addc_u32 s17, s29, 0
	s_add_i32 s23, s23, s73
	global_load_lds_dwordx4 v168, s[28:29]
	s_mov_b32 m0, s23
	s_nop 0
	global_load_lds_dwordx4 v2, s[16:17]
	s_add_i32 m0, s23, 0x2000
	s_nop 0
	global_load_lds_dwordx4 v168, s[16:17]
	s_mov_b32 m0, s74
	s_nop 0
	global_load_lds_dwordx4 v172, vcc
	s_mov_b32 m0, s77
	s_nop 0
	global_load_lds_dwordx4 v170, vcc
	s_waitcnt vmcnt(8)
	s_waitcnt lgkmcnt(0)

	s_barrier
	v_mfma_f32_16x16x32_bf16 v[64:67], v[132:135], v[164:167], v[64:67]
	v_mfma_f32_16x16x32_bf16 v[60:63], v[140:143], v[164:167], v[60:63]
	v_mfma_f32_16x16x32_bf16 v[48:51], v[132:135], v[192:195], v[48:51]
	v_mfma_f32_16x16x32_bf16 v[44:47], v[140:143], v[192:195], v[44:47]
	v_mfma_f32_16x16x32_bf16 v[32:35], v[132:135], v[200:203], v[32:35]
	v_mfma_f32_16x16x32_bf16 v[28:31], v[140:143], v[200:203], v[28:31]
	v_mfma_f32_16x16x32_bf16 v[16:19], v[132:135], v[208:211], v[16:19]
	v_mfma_f32_16x16x32_bf16 v[12:15], v[140:143], v[208:211], v[12:15]
	v_mfma_f32_16x16x32_bf16 v[64:67], v[136:139], v[188:191], v[64:67]
	v_mfma_f32_16x16x32_bf16 v[60:63], v[144:147], v[188:191], v[60:63]
	v_mfma_f32_16x16x32_bf16 v[48:51], v[136:139], v[196:199], v[48:51]
	v_mfma_f32_16x16x32_bf16 v[44:47], v[144:147], v[196:199], v[44:47]
	v_mfma_f32_16x16x32_bf16 v[32:35], v[136:139], v[204:207], v[32:35]
	v_mfma_f32_16x16x32_bf16 v[28:31], v[144:147], v[204:207], v[28:31]
	v_mfma_f32_16x16x32_bf16 v[16:19], v[136:139], v[212:215], v[16:19]
	v_mfma_f32_16x16x32_bf16 v[12:15], v[144:147], v[212:215], v[12:15]
	v_mfma_f32_16x16x32_bf16 v[56:59], v[148:151], v[164:167], v[56:59]
	v_mfma_f32_16x16x32_bf16 v[52:55], v[156:159], v[164:167], v[52:55]
	v_mfma_f32_16x16x32_bf16 v[40:43], v[148:151], v[192:195], v[40:43]
	v_mfma_f32_16x16x32_bf16 v[36:39], v[156:159], v[192:195], v[36:39]
	v_mfma_f32_16x16x32_bf16 v[24:27], v[148:151], v[200:203], v[24:27]
	v_mfma_f32_16x16x32_bf16 v[20:23], v[156:159], v[200:203], v[20:23]
	v_mfma_f32_16x16x32_bf16 v[8:11], v[148:151], v[208:211], v[8:11]
	v_mfma_f32_16x16x32_bf16 v[4:7], v[156:159], v[208:211], v[4:7]
	v_mfma_f32_16x16x32_bf16 v[56:59], v[152:155], v[188:191], v[56:59]
	v_mfma_f32_16x16x32_bf16 v[52:55], v[160:163], v[188:191], v[52:55]
	v_mfma_f32_16x16x32_bf16 v[40:43], v[152:155], v[196:199], v[40:43]
	v_mfma_f32_16x16x32_bf16 v[36:39], v[160:163], v[196:199], v[36:39]
	v_mfma_f32_16x16x32_bf16 v[24:27], v[152:155], v[204:207], v[24:27]
	v_mfma_f32_16x16x32_bf16 v[20:23], v[160:163], v[204:207], v[20:23]
	v_mfma_f32_16x16x32_bf16 v[8:11], v[152:155], v[212:215], v[8:11]
	v_mfma_f32_16x16x32_bf16 v[4:7], v[160:163], v[212:215], v[4:7]
	s_barrier

	s_add_i32 s23, 0, 0x18000
	s_add_i32 s50, 0, 0x1c000
	v_add_u32_e32 v144, s23, v244
	v_add_u32_e32 v160, s50, v244
	ds_read_b128 v[132:135], v144
	ds_read_b128 v[136:139], v144 offset:1024
	ds_read_b128 v[140:143], v144 offset:2048
	ds_read_b128 v[144:147], v144 offset:3072
	ds_read_b128 v[148:151], v160
	ds_read_b128 v[152:155], v160 offset:1024
	ds_read_b128 v[156:159], v160 offset:2048
	ds_read_b128 v[160:163], v160 offset:3072
	s_add_u32 s16, vcc_lo, 0x160000
	s_addc_u32 s17, vcc_hi, 0
	s_mov_b32 m0, s72
	ds_read_b128 v[164:167], v246 offset:32768
	ds_read_b128 v[188:191], v246 offset:33792
	ds_read_b128 v[192:195], v246 offset:34816
	ds_read_b128 v[196:199], v246 offset:35840
	ds_read_b128 v[200:203], v246 offset:36864
	ds_read_b128 v[204:207], v246 offset:37888
	ds_read_b128 v[208:211], v246 offset:38912
	ds_read_b128 v[212:215], v246 offset:39936
	global_load_lds_dwordx4 v172, s[16:17]
	s_mov_b32 m0, s78
	s_nop 0
	global_load_lds_dwordx4 v170, s[16:17]
	s_waitcnt vmcnt(8)
	s_waitcnt lgkmcnt(0)

	s_barrier
	v_mfma_f32_16x16x32_bf16 v[128:131], v[132:135], v[164:167], v[128:131]
	v_mfma_f32_16x16x32_bf16 v[124:127], v[140:143], v[164:167], v[124:127]
	v_mfma_f32_16x16x32_bf16 v[112:115], v[132:135], v[192:195], v[112:115]
	v_mfma_f32_16x16x32_bf16 v[108:111], v[140:143], v[192:195], v[108:111]
	v_mfma_f32_16x16x32_bf16 v[96:99], v[132:135], v[200:203], v[96:99]
	v_mfma_f32_16x16x32_bf16 v[92:95], v[140:143], v[200:203], v[92:95]
	v_mfma_f32_16x16x32_bf16 v[80:83], v[132:135], v[208:211], v[80:83]
	v_mfma_f32_16x16x32_bf16 v[76:79], v[140:143], v[208:211], v[76:79]
	v_mfma_f32_16x16x32_bf16 v[128:131], v[136:139], v[188:191], v[128:131]
	v_mfma_f32_16x16x32_bf16 v[124:127], v[144:147], v[188:191], v[124:127]
	v_mfma_f32_16x16x32_bf16 v[112:115], v[136:139], v[196:199], v[112:115]
	v_mfma_f32_16x16x32_bf16 v[108:111], v[144:147], v[196:199], v[108:111]
	v_mfma_f32_16x16x32_bf16 v[96:99], v[136:139], v[204:207], v[96:99]
	v_mfma_f32_16x16x32_bf16 v[92:95], v[144:147], v[204:207], v[92:95]
	v_mfma_f32_16x16x32_bf16 v[80:83], v[136:139], v[212:215], v[80:83]
	v_mfma_f32_16x16x32_bf16 v[76:79], v[144:147], v[212:215], v[76:79]
	v_mfma_f32_16x16x32_bf16 v[120:123], v[148:151], v[164:167], v[120:123]
	v_mfma_f32_16x16x32_bf16 v[116:119], v[156:159], v[164:167], v[116:119]
	v_mfma_f32_16x16x32_bf16 v[104:107], v[148:151], v[192:195], v[104:107]
	v_mfma_f32_16x16x32_bf16 v[100:103], v[156:159], v[192:195], v[100:103]
	v_mfma_f32_16x16x32_bf16 v[88:91], v[148:151], v[200:203], v[88:91]
	v_mfma_f32_16x16x32_bf16 v[84:87], v[156:159], v[200:203], v[84:87]
	v_mfma_f32_16x16x32_bf16 v[72:75], v[148:151], v[208:211], v[72:75]
	v_mfma_f32_16x16x32_bf16 v[68:71], v[156:159], v[208:211], v[68:71]
	v_mfma_f32_16x16x32_bf16 v[120:123], v[152:155], v[188:191], v[120:123]
	v_mfma_f32_16x16x32_bf16 v[116:119], v[160:163], v[188:191], v[116:119]
	v_mfma_f32_16x16x32_bf16 v[104:107], v[152:155], v[196:199], v[104:107]
	v_mfma_f32_16x16x32_bf16 v[100:103], v[160:163], v[196:199], v[100:103]
	v_mfma_f32_16x16x32_bf16 v[88:91], v[152:155], v[204:207], v[88:91]
	v_mfma_f32_16x16x32_bf16 v[84:87], v[160:163], v[204:207], v[84:87]
	v_mfma_f32_16x16x32_bf16 v[72:75], v[152:155], v[212:215], v[72:75]
	v_mfma_f32_16x16x32_bf16 v[68:71], v[160:163], v[212:215], v[68:71]
	s_barrier

	s_add_i32 s16, s23, s73
	s_mov_b32 m0, s16
	ds_read_b128 v[164:167], v246 offset:49152
	ds_read_b128 v[188:191], v246 offset:50176
	ds_read_b128 v[192:195], v246 offset:51200
	ds_read_b128 v[196:199], v246 offset:52224
	ds_read_b128 v[200:203], v246 offset:53248
	ds_read_b128 v[204:207], v246 offset:54272
	ds_read_b128 v[208:211], v246 offset:55296
	ds_read_b128 v[212:215], v246 offset:56320
	s_add_u32 s100, s28, s24
	s_addc_u32 s101, s29, s25
	global_load_lds_dwordx4 v2, s[100:101]
	s_add_i32 m0, s16, 0x2000
	s_add_u32 s16, s28, 0x58080
	s_addc_u32 s17, s29, 0
	s_add_i32 s23, s50, s73
	global_load_lds_dwordx4 v168, s[100:101]
	s_mov_b32 m0, s23
	s_nop 0
	global_load_lds_dwordx4 v2, s[16:17]
	s_add_i32 m0, s23, 0x2000
	s_nop 0
	global_load_lds_dwordx4 v168, s[16:17]
	s_mov_b32 m0, s36
	s_nop 0
	s_add_u32 s100, vcc_lo, s24
	s_addc_u32 s101, vcc_hi, s25
	global_load_lds_dwordx4 v172, s[100:101]
	s_mov_b32 m0, s37
	s_nop 0
	global_load_lds_dwordx4 v170, s[100:101]
	s_waitcnt vmcnt(8)
	s_waitcnt lgkmcnt(0)

	s_barrier
	v_mfma_f32_16x16x32_bf16 v[64:67], v[132:135], v[164:167], v[64:67]
	v_mfma_f32_16x16x32_bf16 v[60:63], v[140:143], v[164:167], v[60:63]
	v_mfma_f32_16x16x32_bf16 v[48:51], v[132:135], v[192:195], v[48:51]
	v_mfma_f32_16x16x32_bf16 v[44:47], v[140:143], v[192:195], v[44:47]
	v_mfma_f32_16x16x32_bf16 v[32:35], v[132:135], v[200:203], v[32:35]
	v_mfma_f32_16x16x32_bf16 v[28:31], v[140:143], v[200:203], v[28:31]
	v_mfma_f32_16x16x32_bf16 v[16:19], v[132:135], v[208:211], v[16:19]
	v_mfma_f32_16x16x32_bf16 v[12:15], v[140:143], v[208:211], v[12:15]
	v_mfma_f32_16x16x32_bf16 v[64:67], v[136:139], v[188:191], v[64:67]
	v_mfma_f32_16x16x32_bf16 v[60:63], v[144:147], v[188:191], v[60:63]
	v_mfma_f32_16x16x32_bf16 v[48:51], v[136:139], v[196:199], v[48:51]
	v_mfma_f32_16x16x32_bf16 v[44:47], v[144:147], v[196:199], v[44:47]
	v_mfma_f32_16x16x32_bf16 v[32:35], v[136:139], v[204:207], v[32:35]
	v_mfma_f32_16x16x32_bf16 v[28:31], v[144:147], v[204:207], v[28:31]
	v_mfma_f32_16x16x32_bf16 v[16:19], v[136:139], v[212:215], v[16:19]
	v_mfma_f32_16x16x32_bf16 v[12:15], v[144:147], v[212:215], v[12:15]
	v_mfma_f32_16x16x32_bf16 v[56:59], v[148:151], v[164:167], v[56:59]
	v_mfma_f32_16x16x32_bf16 v[52:55], v[156:159], v[164:167], v[52:55]
	v_mfma_f32_16x16x32_bf16 v[40:43], v[148:151], v[192:195], v[40:43]
	v_mfma_f32_16x16x32_bf16 v[36:39], v[156:159], v[192:195], v[36:39]
	v_mfma_f32_16x16x32_bf16 v[24:27], v[148:151], v[200:203], v[24:27]
	v_mfma_f32_16x16x32_bf16 v[20:23], v[156:159], v[200:203], v[20:23]
	v_mfma_f32_16x16x32_bf16 v[8:11], v[148:151], v[208:211], v[8:11]
	v_mfma_f32_16x16x32_bf16 v[4:7], v[156:159], v[208:211], v[4:7]
	v_mfma_f32_16x16x32_bf16 v[56:59], v[152:155], v[188:191], v[56:59]
	v_mfma_f32_16x16x32_bf16 v[52:55], v[160:163], v[188:191], v[52:55]
	v_mfma_f32_16x16x32_bf16 v[40:43], v[152:155], v[196:199], v[40:43]
	v_mfma_f32_16x16x32_bf16 v[36:39], v[160:163], v[196:199], v[36:39]
	v_mfma_f32_16x16x32_bf16 v[24:27], v[152:155], v[204:207], v[24:27]
	v_mfma_f32_16x16x32_bf16 v[20:23], v[160:163], v[204:207], v[20:23]
	v_mfma_f32_16x16x32_bf16 v[8:11], v[152:155], v[212:215], v[8:11]
	v_mfma_f32_16x16x32_bf16 v[4:7], v[160:163], v[212:215], v[4:7]
	s_barrier

	s_add_i32 s22, s22, 2
	s_add_u32 s31, s31, 0x100
	s_addc_u32 s33, s33, 0
	s_cmpk_gt_u32 s22, 0x55
	s_mov_b64 s[50:51], s[48:49]
	s_cbranch_scc0 .LBB0_366
	s_setprio 0
	v_readlane_b32 s16, v252, 12
	v_readlane_b32 s17, v252, 13

.Lsp_446:
.LBB0_446:
	s_add_u32 s16, s44, 0xfff80080
	s_addc_u32 s17, s45, -1
	s_add_i32 s94, 0, 0x10000
	s_cmp_eq_u32 vcc_lo, 28
	s_cselect_b32 s47, s37, s17
	s_cselect_b32 s46, s88, s16
	s_cselect_b32 s29, s27, s96
	s_cselect_b32 s28, s89, s91
	s_add_i32 s95, 0, 0x14000
	v_add_u32_e32 v144, s94, v219
	v_add_u32_e32 v172, s95, v219
	ds_read_b128 v[132:135], v144
	ds_read_b128 v[136:139], v144 offset:1024
	ds_read_b128 v[140:143], v144 offset:2048
	ds_read_b128 v[144:147], v144 offset:3072
	ds_read_b128 v[148:151], v172
	ds_read_b128 v[164:167], v172 offset:1024
	ds_read_b128 v[168:171], v172 offset:2048
	ds_read_b128 v[184:187], v172 offset:3072
	s_add_i32 m0, s48, 0xc000
	ds_read_b128 v[188:191], v221
	ds_read_b128 v[192:195], v221 offset:1024
	ds_read_b128 v[196:199], v221 offset:2048
	ds_read_b128 v[200:203], v221 offset:3072
	ds_read_b128 v[204:207], v221 offset:4096
	ds_read_b128 v[208:211], v221 offset:5120
	ds_read_b128 v[212:215], v221 offset:6144
	ds_read_b128 v[222:225], v221 offset:7168
	global_load_lds_dwordx4 v160, s[44:45]
	s_add_i32 m0, s48, 0xe000
	s_nop 0
	global_load_lds_dwordx4 v162, s[44:45]
	s_waitcnt vmcnt(8)
	s_waitcnt lgkmcnt(0)

	s_barrier
	v_mfma_f32_16x16x32_bf16 v[128:131], v[132:135], v[188:191], v[128:131]
	v_mfma_f32_16x16x32_bf16 v[124:127], v[140:143], v[188:191], v[124:127]
	v_mfma_f32_16x16x32_bf16 v[112:115], v[132:135], v[196:199], v[112:115]
	v_mfma_f32_16x16x32_bf16 v[108:111], v[140:143], v[196:199], v[108:111]
	v_mfma_f32_16x16x32_bf16 v[96:99], v[132:135], v[204:207], v[96:99]
	v_mfma_f32_16x16x32_bf16 v[92:95], v[140:143], v[204:207], v[92:95]
	v_mfma_f32_16x16x32_bf16 v[80:83], v[132:135], v[212:215], v[80:83]
	v_mfma_f32_16x16x32_bf16 v[76:79], v[140:143], v[212:215], v[76:79]
	v_mfma_f32_16x16x32_bf16 v[128:131], v[136:139], v[192:195], v[128:131]
	v_mfma_f32_16x16x32_bf16 v[124:127], v[144:147], v[192:195], v[124:127]
	v_mfma_f32_16x16x32_bf16 v[112:115], v[136:139], v[200:203], v[112:115]
	v_mfma_f32_16x16x32_bf16 v[108:111], v[144:147], v[200:203], v[108:111]
	v_mfma_f32_16x16x32_bf16 v[96:99], v[136:139], v[208:211], v[96:99]
	v_mfma_f32_16x16x32_bf16 v[92:95], v[144:147], v[208:211], v[92:95]
	v_mfma_f32_16x16x32_bf16 v[80:83], v[136:139], v[222:225], v[80:83]
	v_mfma_f32_16x16x32_bf16 v[76:79], v[144:147], v[222:225], v[76:79]
	v_mfma_f32_16x16x32_bf16 v[120:123], v[148:151], v[188:191], v[120:123]
	v_mfma_f32_16x16x32_bf16 v[116:119], v[168:171], v[188:191], v[116:119]
	v_mfma_f32_16x16x32_bf16 v[104:107], v[148:151], v[196:199], v[104:107]
	v_mfma_f32_16x16x32_bf16 v[100:103], v[168:171], v[196:199], v[100:103]
	v_mfma_f32_16x16x32_bf16 v[88:91], v[148:151], v[204:207], v[88:91]
	v_mfma_f32_16x16x32_bf16 v[84:87], v[168:171], v[204:207], v[84:87]
	v_mfma_f32_16x16x32_bf16 v[72:75], v[148:151], v[212:215], v[72:75]
	v_mfma_f32_16x16x32_bf16 v[68:71], v[168:171], v[212:215], v[68:71]
	v_mfma_f32_16x16x32_bf16 v[120:123], v[164:167], v[192:195], v[120:123]
	v_mfma_f32_16x16x32_bf16 v[116:119], v[184:187], v[192:195], v[116:119]
	v_mfma_f32_16x16x32_bf16 v[104:107], v[164:167], v[200:203], v[104:107]
	v_mfma_f32_16x16x32_bf16 v[100:103], v[184:187], v[200:203], v[100:103]
	v_mfma_f32_16x16x32_bf16 v[88:91], v[164:167], v[208:211], v[88:91]
	v_mfma_f32_16x16x32_bf16 v[84:87], v[184:187], v[208:211], v[84:87]
	v_mfma_f32_16x16x32_bf16 v[72:75], v[164:167], v[222:225], v[72:75]
	v_mfma_f32_16x16x32_bf16 v[68:71], v[184:187], v[222:225], v[68:71]
	s_barrier

	s_add_i32 s16, s94, s33
	s_mov_b32 m0, s16
	ds_read_b128 v[188:191], v221 offset:16384
	ds_read_b128 v[192:195], v221 offset:17408
	ds_read_b128 v[196:199], v221 offset:18432
	ds_read_b128 v[200:203], v221 offset:19456
	ds_read_b128 v[204:207], v221 offset:20480
	ds_read_b128 v[208:211], v221 offset:21504
	ds_read_b128 v[212:215], v221 offset:22528
	ds_read_b128 v[222:225], v221 offset:23552
	global_load_lds_dwordx4 v2, s[28:29]
	s_add_i32 m0, s16, 0x2000
	s_add_u32 s16, s28, 0x80000
	s_addc_u32 s17, s29, 0
	s_add_i32 s94, s95, s33
	global_load_lds_dwordx4 v152, s[28:29]
	s_mov_b32 m0, s94
	s_nop 0
	global_load_lds_dwordx4 v2, s[16:17]
	s_add_i32 m0, s94, 0x2000
	s_nop 0
	global_load_lds_dwordx4 v152, s[16:17]
	s_mov_b32 m0, s48
	s_nop 0
	global_load_lds_dwordx4 v156, s[46:47]
	s_mov_b32 m0, s49
	s_nop 0
	global_load_lds_dwordx4 v154, s[46:47]
	s_waitcnt vmcnt(8)
	s_waitcnt lgkmcnt(0)

	s_barrier
	v_mfma_f32_16x16x32_bf16 v[64:67], v[132:135], v[188:191], v[64:67]
	v_mfma_f32_16x16x32_bf16 v[60:63], v[140:143], v[188:191], v[60:63]
	v_mfma_f32_16x16x32_bf16 v[48:51], v[132:135], v[196:199], v[48:51]
	v_mfma_f32_16x16x32_bf16 v[44:47], v[140:143], v[196:199], v[44:47]
	v_mfma_f32_16x16x32_bf16 v[32:35], v[132:135], v[204:207], v[32:35]
	v_mfma_f32_16x16x32_bf16 v[28:31], v[140:143], v[204:207], v[28:31]
	v_mfma_f32_16x16x32_bf16 v[16:19], v[132:135], v[212:215], v[16:19]
	v_mfma_f32_16x16x32_bf16 v[12:15], v[140:143], v[212:215], v[12:15]
	v_mfma_f32_16x16x32_bf16 v[64:67], v[136:139], v[192:195], v[64:67]
	v_mfma_f32_16x16x32_bf16 v[60:63], v[144:147], v[192:195], v[60:63]
	v_mfma_f32_16x16x32_bf16 v[48:51], v[136:139], v[200:203], v[48:51]
	v_mfma_f32_16x16x32_bf16 v[44:47], v[144:147], v[200:203], v[44:47]
	v_mfma_f32_16x16x32_bf16 v[32:35], v[136:139], v[208:211], v[32:35]
	v_mfma_f32_16x16x32_bf16 v[28:31], v[144:147], v[208:211], v[28:31]
	v_mfma_f32_16x16x32_bf16 v[16:19], v[136:139], v[222:225], v[16:19]
	v_mfma_f32_16x16x32_bf16 v[12:15], v[144:147], v[222:225], v[12:15]
	v_mfma_f32_16x16x32_bf16 v[56:59], v[148:151], v[188:191], v[56:59]
	v_mfma_f32_16x16x32_bf16 v[52:55], v[168:171], v[188:191], v[52:55]
	v_mfma_f32_16x16x32_bf16 v[40:43], v[148:151], v[196:199], v[40:43]
	v_mfma_f32_16x16x32_bf16 v[36:39], v[168:171], v[196:199], v[36:39]
	v_mfma_f32_16x16x32_bf16 v[24:27], v[148:151], v[204:207], v[24:27]
	v_mfma_f32_16x16x32_bf16 v[20:23], v[168:171], v[204:207], v[20:23]
	v_mfma_f32_16x16x32_bf16 v[8:11], v[148:151], v[212:215], v[8:11]
	v_mfma_f32_16x16x32_bf16 v[4:7], v[168:171], v[212:215], v[4:7]
	v_mfma_f32_16x16x32_bf16 v[56:59], v[164:167], v[192:195], v[56:59]
	v_mfma_f32_16x16x32_bf16 v[52:55], v[184:187], v[192:195], v[52:55]
	v_mfma_f32_16x16x32_bf16 v[40:43], v[164:167], v[200:203], v[40:43]
	v_mfma_f32_16x16x32_bf16 v[36:39], v[184:187], v[200:203], v[36:39]
	v_mfma_f32_16x16x32_bf16 v[24:27], v[164:167], v[208:211], v[24:27]
	v_mfma_f32_16x16x32_bf16 v[20:23], v[184:187], v[208:211], v[20:23]
	v_mfma_f32_16x16x32_bf16 v[8:11], v[164:167], v[222:225], v[8:11]
	v_mfma_f32_16x16x32_bf16 v[4:7], v[184:187], v[222:225], v[4:7]
	s_barrier

	s_add_i32 s94, 0, 0x18000
	s_add_i32 s95, 0, 0x1c000
	v_add_u32_e32 v144, s94, v219
	v_add_u32_e32 v176, s95, v219
	ds_read_b128 v[132:135], v144
	ds_read_b128 v[136:139], v144 offset:1024
	ds_read_b128 v[140:143], v144 offset:2048
	ds_read_b128 v[144:147], v144 offset:3072
	ds_read_b128 v[148:151], v176
	ds_read_b128 v[164:167], v176 offset:1024
	ds_read_b128 v[168:171], v176 offset:2048
	ds_read_b128 v[184:187], v176 offset:3072
	s_add_u32 s16, s46, 0x80000
	s_addc_u32 s17, s47, 0
	s_mov_b32 m0, s50
	ds_read_b128 v[188:191], v221 offset:32768
	ds_read_b128 v[192:195], v221 offset:33792
	ds_read_b128 v[196:199], v221 offset:34816
	ds_read_b128 v[200:203], v221 offset:35840
	ds_read_b128 v[204:207], v221 offset:36864
	ds_read_b128 v[208:211], v221 offset:37888
	ds_read_b128 v[212:215], v221 offset:38912
	ds_read_b128 v[222:225], v221 offset:39936
	global_load_lds_dwordx4 v156, s[16:17]
	s_mov_b32 m0, s51
	s_nop 0
	global_load_lds_dwordx4 v154, s[16:17]
	s_waitcnt vmcnt(8)
	s_waitcnt lgkmcnt(0)

	s_barrier
	v_mfma_f32_16x16x32_bf16 v[128:131], v[132:135], v[188:191], v[128:131]
	v_mfma_f32_16x16x32_bf16 v[124:127], v[140:143], v[188:191], v[124:127]
	v_mfma_f32_16x16x32_bf16 v[112:115], v[132:135], v[196:199], v[112:115]
	v_mfma_f32_16x16x32_bf16 v[108:111], v[140:143], v[196:199], v[108:111]
	v_mfma_f32_16x16x32_bf16 v[96:99], v[132:135], v[204:207], v[96:99]
	v_mfma_f32_16x16x32_bf16 v[92:95], v[140:143], v[204:207], v[92:95]
	v_mfma_f32_16x16x32_bf16 v[80:83], v[132:135], v[212:215], v[80:83]
	v_mfma_f32_16x16x32_bf16 v[76:79], v[140:143], v[212:215], v[76:79]
	v_mfma_f32_16x16x32_bf16 v[128:131], v[136:139], v[192:195], v[128:131]
	v_mfma_f32_16x16x32_bf16 v[124:127], v[144:147], v[192:195], v[124:127]
	v_mfma_f32_16x16x32_bf16 v[112:115], v[136:139], v[200:203], v[112:115]
	v_mfma_f32_16x16x32_bf16 v[108:111], v[144:147], v[200:203], v[108:111]
	v_mfma_f32_16x16x32_bf16 v[96:99], v[136:139], v[208:211], v[96:99]
	v_mfma_f32_16x16x32_bf16 v[92:95], v[144:147], v[208:211], v[92:95]
	v_mfma_f32_16x16x32_bf16 v[80:83], v[136:139], v[222:225], v[80:83]
	v_mfma_f32_16x16x32_bf16 v[76:79], v[144:147], v[222:225], v[76:79]
	v_mfma_f32_16x16x32_bf16 v[120:123], v[148:151], v[188:191], v[120:123]
	v_mfma_f32_16x16x32_bf16 v[116:119], v[168:171], v[188:191], v[116:119]
	v_mfma_f32_16x16x32_bf16 v[104:107], v[148:151], v[196:199], v[104:107]
	v_mfma_f32_16x16x32_bf16 v[100:103], v[168:171], v[196:199], v[100:103]
	v_mfma_f32_16x16x32_bf16 v[88:91], v[148:151], v[204:207], v[88:91]
	v_mfma_f32_16x16x32_bf16 v[84:87], v[168:171], v[204:207], v[84:87]
	v_mfma_f32_16x16x32_bf16 v[72:75], v[148:151], v[212:215], v[72:75]
	v_mfma_f32_16x16x32_bf16 v[68:71], v[168:171], v[212:215], v[68:71]
	v_mfma_f32_16x16x32_bf16 v[120:123], v[164:167], v[192:195], v[120:123]
	v_mfma_f32_16x16x32_bf16 v[116:119], v[184:187], v[192:195], v[116:119]
	v_mfma_f32_16x16x32_bf16 v[104:107], v[164:167], v[200:203], v[104:107]
	v_mfma_f32_16x16x32_bf16 v[100:103], v[184:187], v[200:203], v[100:103]
	v_mfma_f32_16x16x32_bf16 v[88:91], v[164:167], v[208:211], v[88:91]
	v_mfma_f32_16x16x32_bf16 v[84:87], v[184:187], v[208:211], v[84:87]
	v_mfma_f32_16x16x32_bf16 v[72:75], v[164:167], v[222:225], v[72:75]
	v_mfma_f32_16x16x32_bf16 v[68:71], v[184:187], v[222:225], v[68:71]
	s_barrier

	s_add_i32 s16, s94, s33
	s_mov_b32 m0, s16
	ds_read_b128 v[188:191], v221 offset:49152
	ds_read_b128 v[192:195], v221 offset:50176
	ds_read_b128 v[196:199], v221 offset:51200
	ds_read_b128 v[200:203], v221 offset:52224
	ds_read_b128 v[204:207], v221 offset:53248
	ds_read_b128 v[208:211], v221 offset:54272
	ds_read_b128 v[212:215], v221 offset:55296
	ds_read_b128 v[222:225], v221 offset:56320
	s_add_u32 s100, s28, s24
	s_addc_u32 s101, s29, s25
	global_load_lds_dwordx4 v2, s[100:101]
	s_add_i32 m0, s16, 0x2000
	s_add_u32 s16, s28, 0x80080
	s_addc_u32 s17, s29, 0
	s_add_i32 s28, s95, s33
	global_load_lds_dwordx4 v152, s[100:101]
	s_mov_b32 m0, s28
	s_nop 0
	global_load_lds_dwordx4 v2, s[16:17]
	s_add_i32 m0, s28, 0x2000
	s_nop 0
	global_load_lds_dwordx4 v152, s[16:17]
	s_mov_b32 m0, s72
	s_nop 0
	s_add_u32 s100, s46, s24
	s_addc_u32 s101, s47, s25
	global_load_lds_dwordx4 v156, s[100:101]
	s_mov_b32 m0, s73
	s_nop 0
	global_load_lds_dwordx4 v154, s[100:101]
	s_waitcnt vmcnt(8)
	s_waitcnt lgkmcnt(0)

	s_barrier
	v_mfma_f32_16x16x32_bf16 v[64:67], v[132:135], v[188:191], v[64:67]
	v_mfma_f32_16x16x32_bf16 v[60:63], v[140:143], v[188:191], v[60:63]
	v_mfma_f32_16x16x32_bf16 v[48:51], v[132:135], v[196:199], v[48:51]
	v_mfma_f32_16x16x32_bf16 v[44:47], v[140:143], v[196:199], v[44:47]
	v_mfma_f32_16x16x32_bf16 v[32:35], v[132:135], v[204:207], v[32:35]
	v_mfma_f32_16x16x32_bf16 v[28:31], v[140:143], v[204:207], v[28:31]
	v_mfma_f32_16x16x32_bf16 v[16:19], v[132:135], v[212:215], v[16:19]
	v_mfma_f32_16x16x32_bf16 v[12:15], v[140:143], v[212:215], v[12:15]
	v_mfma_f32_16x16x32_bf16 v[64:67], v[136:139], v[192:195], v[64:67]
	v_mfma_f32_16x16x32_bf16 v[60:63], v[144:147], v[192:195], v[60:63]
	v_mfma_f32_16x16x32_bf16 v[48:51], v[136:139], v[200:203], v[48:51]
	v_mfma_f32_16x16x32_bf16 v[44:47], v[144:147], v[200:203], v[44:47]
	v_mfma_f32_16x16x32_bf16 v[32:35], v[136:139], v[208:211], v[32:35]
	v_mfma_f32_16x16x32_bf16 v[28:31], v[144:147], v[208:211], v[28:31]
	v_mfma_f32_16x16x32_bf16 v[16:19], v[136:139], v[222:225], v[16:19]
	v_mfma_f32_16x16x32_bf16 v[12:15], v[144:147], v[222:225], v[12:15]
	v_mfma_f32_16x16x32_bf16 v[56:59], v[148:151], v[188:191], v[56:59]
	v_mfma_f32_16x16x32_bf16 v[52:55], v[168:171], v[188:191], v[52:55]
	v_mfma_f32_16x16x32_bf16 v[40:43], v[148:151], v[196:199], v[40:43]
	v_mfma_f32_16x16x32_bf16 v[36:39], v[168:171], v[196:199], v[36:39]
	v_mfma_f32_16x16x32_bf16 v[24:27], v[148:151], v[204:207], v[24:27]
	v_mfma_f32_16x16x32_bf16 v[20:23], v[168:171], v[204:207], v[20:23]
	v_mfma_f32_16x16x32_bf16 v[8:11], v[148:151], v[212:215], v[8:11]
	v_mfma_f32_16x16x32_bf16 v[4:7], v[168:171], v[212:215], v[4:7]
	v_mfma_f32_16x16x32_bf16 v[56:59], v[164:167], v[192:195], v[56:59]
	v_mfma_f32_16x16x32_bf16 v[52:55], v[184:187], v[192:195], v[52:55]
	v_mfma_f32_16x16x32_bf16 v[40:43], v[164:167], v[200:203], v[40:43]
	v_mfma_f32_16x16x32_bf16 v[36:39], v[184:187], v[200:203], v[36:39]
	v_mfma_f32_16x16x32_bf16 v[24:27], v[164:167], v[208:211], v[24:27]
	v_mfma_f32_16x16x32_bf16 v[20:23], v[184:187], v[208:211], v[20:23]
	v_mfma_f32_16x16x32_bf16 v[8:11], v[164:167], v[222:225], v[8:11]
	v_mfma_f32_16x16x32_bf16 v[4:7], v[184:187], v[222:225], v[4:7]
	s_barrier

	s_add_i32 vcc_lo, vcc_lo, 2
	s_add_u32 s44, s44, 0x100
	s_addc_u32 s45, s45, 0
	s_add_u32 s91, s91, 0x100
	s_addc_u32 s96, s96, 0
	s_cmp_gt_u32 vcc_lo, 29
	s_cbranch_scc0 .LBB0_446
	s_setprio 0
	v_mov_b32_e32 v250, 0xc2000000
	v_mov_b32_e32 v1, 0xbfb8aa3b
	v_mov_b64_e32 v[238:239], v[236:237]

.Lsp_790:
.LBB0_790:
	s_add_u32 s11, vcc_lo, 0xfff80080
	s_addc_u32 s16, vcc_hi, -1
	s_add_i32 s17, 0, 0x10000
	s_cmp_eq_u32 s10, 28
	s_cselect_b32 s73, s19, s16
	s_cselect_b32 s72, s31, s11
	s_cselect_b32 s29, s23, s49
	s_cselect_b32 s28, s33, s48
	s_add_i32 s11, 0, 0x14000
	v_add_u32_e32 v144, s17, v244
	v_add_u32_e32 v160, s11, v244
	ds_read_b128 v[132:135], v144
	ds_read_b128 v[136:139], v144 offset:1024
	ds_read_b128 v[140:143], v144 offset:2048
	ds_read_b128 v[144:147], v144 offset:3072
	ds_read_b128 v[148:151], v160
	ds_read_b128 v[152:155], v160 offset:1024
	ds_read_b128 v[156:159], v160 offset:2048
	ds_read_b128 v[160:163], v160 offset:3072
	s_add_i32 m0, s77, 0xc000
	ds_read_b128 v[164:167], v246
	ds_read_b128 v[188:191], v246 offset:1024
	ds_read_b128 v[192:195], v246 offset:2048
	ds_read_b128 v[196:199], v246 offset:3072
	ds_read_b128 v[200:203], v246 offset:4096
	ds_read_b128 v[204:207], v246 offset:5120
	ds_read_b128 v[208:211], v246 offset:6144
	ds_read_b128 v[212:215], v246 offset:7168
	global_load_lds_dwordx4 v184, vcc
	s_add_i32 m0, s77, 0xe000
	s_nop 0
	global_load_lds_dwordx4 v186, vcc
	s_waitcnt vmcnt(8)
	s_waitcnt lgkmcnt(0)

	s_barrier
	v_mfma_f32_16x16x32_bf16 v[128:131], v[132:135], v[164:167], v[128:131]
	v_mfma_f32_16x16x32_bf16 v[124:127], v[140:143], v[164:167], v[124:127]
	v_mfma_f32_16x16x32_bf16 v[112:115], v[132:135], v[192:195], v[112:115]
	v_mfma_f32_16x16x32_bf16 v[108:111], v[140:143], v[192:195], v[108:111]
	v_mfma_f32_16x16x32_bf16 v[96:99], v[132:135], v[200:203], v[96:99]
	v_mfma_f32_16x16x32_bf16 v[92:95], v[140:143], v[200:203], v[92:95]
	v_mfma_f32_16x16x32_bf16 v[80:83], v[132:135], v[208:211], v[80:83]
	v_mfma_f32_16x16x32_bf16 v[76:79], v[140:143], v[208:211], v[76:79]
	v_mfma_f32_16x16x32_bf16 v[128:131], v[136:139], v[188:191], v[128:131]
	v_mfma_f32_16x16x32_bf16 v[124:127], v[144:147], v[188:191], v[124:127]
	v_mfma_f32_16x16x32_bf16 v[112:115], v[136:139], v[196:199], v[112:115]
	v_mfma_f32_16x16x32_bf16 v[108:111], v[144:147], v[196:199], v[108:111]
	v_mfma_f32_16x16x32_bf16 v[96:99], v[136:139], v[204:207], v[96:99]
	v_mfma_f32_16x16x32_bf16 v[92:95], v[144:147], v[204:207], v[92:95]
	v_mfma_f32_16x16x32_bf16 v[80:83], v[136:139], v[212:215], v[80:83]
	v_mfma_f32_16x16x32_bf16 v[76:79], v[144:147], v[212:215], v[76:79]
	v_mfma_f32_16x16x32_bf16 v[120:123], v[148:151], v[164:167], v[120:123]
	v_mfma_f32_16x16x32_bf16 v[116:119], v[156:159], v[164:167], v[116:119]
	v_mfma_f32_16x16x32_bf16 v[104:107], v[148:151], v[192:195], v[104:107]
	v_mfma_f32_16x16x32_bf16 v[100:103], v[156:159], v[192:195], v[100:103]
	v_mfma_f32_16x16x32_bf16 v[88:91], v[148:151], v[200:203], v[88:91]
	v_mfma_f32_16x16x32_bf16 v[84:87], v[156:159], v[200:203], v[84:87]
	v_mfma_f32_16x16x32_bf16 v[72:75], v[148:151], v[208:211], v[72:75]
	v_mfma_f32_16x16x32_bf16 v[68:71], v[156:159], v[208:211], v[68:71]
	v_mfma_f32_16x16x32_bf16 v[120:123], v[152:155], v[188:191], v[120:123]
	v_mfma_f32_16x16x32_bf16 v[116:119], v[160:163], v[188:191], v[116:119]
	v_mfma_f32_16x16x32_bf16 v[104:107], v[152:155], v[196:199], v[104:107]
	v_mfma_f32_16x16x32_bf16 v[100:103], v[160:163], v[196:199], v[100:103]
	v_mfma_f32_16x16x32_bf16 v[88:91], v[152:155], v[204:207], v[88:91]
	v_mfma_f32_16x16x32_bf16 v[84:87], v[160:163], v[204:207], v[84:87]
	v_mfma_f32_16x16x32_bf16 v[72:75], v[152:155], v[212:215], v[72:75]
	v_mfma_f32_16x16x32_bf16 v[68:71], v[160:163], v[212:215], v[68:71]
	s_barrier

	s_add_i32 s16, s17, s74
	s_mov_b32 m0, s16
	ds_read_b128 v[164:167], v246 offset:16384
	ds_read_b128 v[188:191], v246 offset:17408
	ds_read_b128 v[192:195], v246 offset:18432
	ds_read_b128 v[196:199], v246 offset:19456
	ds_read_b128 v[200:203], v246 offset:20480
	ds_read_b128 v[204:207], v246 offset:21504
	ds_read_b128 v[208:211], v246 offset:22528
	ds_read_b128 v[212:215], v246 offset:23552
	global_load_lds_dwordx4 v2, s[28:29]
	s_add_i32 m0, s16, 0x2000
	s_add_u32 s16, s28, 0x20000
	s_addc_u32 s17, s29, 0
	s_add_i32 s11, s11, s74
	global_load_lds_dwordx4 v168, s[28:29]
	s_mov_b32 m0, s11
	s_nop 0
	global_load_lds_dwordx4 v2, s[16:17]
	s_add_i32 m0, s11, 0x2000
	s_nop 0
	global_load_lds_dwordx4 v168, s[16:17]
	s_mov_b32 m0, s77
	s_nop 0
	global_load_lds_dwordx4 v172, s[72:73]
	s_mov_b32 m0, s78
	s_nop 0
	global_load_lds_dwordx4 v170, s[72:73]
	s_waitcnt vmcnt(8)
	s_waitcnt lgkmcnt(0)

	s_barrier
	v_mfma_f32_16x16x32_bf16 v[64:67], v[132:135], v[164:167], v[64:67]
	v_mfma_f32_16x16x32_bf16 v[60:63], v[140:143], v[164:167], v[60:63]
	v_mfma_f32_16x16x32_bf16 v[48:51], v[132:135], v[192:195], v[48:51]
	v_mfma_f32_16x16x32_bf16 v[44:47], v[140:143], v[192:195], v[44:47]
	v_mfma_f32_16x16x32_bf16 v[32:35], v[132:135], v[200:203], v[32:35]
	v_mfma_f32_16x16x32_bf16 v[28:31], v[140:143], v[200:203], v[28:31]
	v_mfma_f32_16x16x32_bf16 v[16:19], v[132:135], v[208:211], v[16:19]
	v_mfma_f32_16x16x32_bf16 v[12:15], v[140:143], v[208:211], v[12:15]
	v_mfma_f32_16x16x32_bf16 v[64:67], v[136:139], v[188:191], v[64:67]
	v_mfma_f32_16x16x32_bf16 v[60:63], v[144:147], v[188:191], v[60:63]
	v_mfma_f32_16x16x32_bf16 v[48:51], v[136:139], v[196:199], v[48:51]
	v_mfma_f32_16x16x32_bf16 v[44:47], v[144:147], v[196:199], v[44:47]
	v_mfma_f32_16x16x32_bf16 v[32:35], v[136:139], v[204:207], v[32:35]
	v_mfma_f32_16x16x32_bf16 v[28:31], v[144:147], v[204:207], v[28:31]
	v_mfma_f32_16x16x32_bf16 v[16:19], v[136:139], v[212:215], v[16:19]
	v_mfma_f32_16x16x32_bf16 v[12:15], v[144:147], v[212:215], v[12:15]
	v_mfma_f32_16x16x32_bf16 v[56:59], v[148:151], v[164:167], v[56:59]
	v_mfma_f32_16x16x32_bf16 v[52:55], v[156:159], v[164:167], v[52:55]
	v_mfma_f32_16x16x32_bf16 v[40:43], v[148:151], v[192:195], v[40:43]
	v_mfma_f32_16x16x32_bf16 v[36:39], v[156:159], v[192:195], v[36:39]
	v_mfma_f32_16x16x32_bf16 v[24:27], v[148:151], v[200:203], v[24:27]
	v_mfma_f32_16x16x32_bf16 v[20:23], v[156:159], v[200:203], v[20:23]
	v_mfma_f32_16x16x32_bf16 v[8:11], v[148:151], v[208:211], v[8:11]
	v_mfma_f32_16x16x32_bf16 v[4:7], v[156:159], v[208:211], v[4:7]
	v_mfma_f32_16x16x32_bf16 v[56:59], v[152:155], v[188:191], v[56:59]
	v_mfma_f32_16x16x32_bf16 v[52:55], v[160:163], v[188:191], v[52:55]
	v_mfma_f32_16x16x32_bf16 v[40:43], v[152:155], v[196:199], v[40:43]
	v_mfma_f32_16x16x32_bf16 v[36:39], v[160:163], v[196:199], v[36:39]
	v_mfma_f32_16x16x32_bf16 v[24:27], v[152:155], v[204:207], v[24:27]
	v_mfma_f32_16x16x32_bf16 v[20:23], v[160:163], v[204:207], v[20:23]
	v_mfma_f32_16x16x32_bf16 v[8:11], v[152:155], v[212:215], v[8:11]
	v_mfma_f32_16x16x32_bf16 v[4:7], v[160:163], v[212:215], v[4:7]
	s_barrier

	s_add_i32 s11, 0, 0x18000
	s_add_i32 s94, 0, 0x1c000
	v_add_u32_e32 v144, s11, v244
	v_add_u32_e32 v160, s94, v244
	ds_read_b128 v[132:135], v144
	ds_read_b128 v[136:139], v144 offset:1024
	ds_read_b128 v[140:143], v144 offset:2048
	ds_read_b128 v[144:147], v144 offset:3072
	ds_read_b128 v[148:151], v160
	ds_read_b128 v[152:155], v160 offset:1024
	ds_read_b128 v[156:159], v160 offset:2048
	ds_read_b128 v[160:163], v160 offset:3072
	s_add_u32 s16, s72, 0x80000
	s_addc_u32 s17, s73, 0
	s_mov_b32 m0, s95
	ds_read_b128 v[164:167], v246 offset:32768
	ds_read_b128 v[188:191], v246 offset:33792
	ds_read_b128 v[192:195], v246 offset:34816
	ds_read_b128 v[196:199], v246 offset:35840
	ds_read_b128 v[200:203], v246 offset:36864
	ds_read_b128 v[204:207], v246 offset:37888
	ds_read_b128 v[208:211], v246 offset:38912
	ds_read_b128 v[212:215], v246 offset:39936
	global_load_lds_dwordx4 v172, s[16:17]
	s_mov_b32 m0, s68
	s_nop 0
	global_load_lds_dwordx4 v170, s[16:17]
	s_waitcnt vmcnt(8)
	s_waitcnt lgkmcnt(0)

	s_barrier
	v_mfma_f32_16x16x32_bf16 v[128:131], v[132:135], v[164:167], v[128:131]
	v_mfma_f32_16x16x32_bf16 v[124:127], v[140:143], v[164:167], v[124:127]
	v_mfma_f32_16x16x32_bf16 v[112:115], v[132:135], v[192:195], v[112:115]
	v_mfma_f32_16x16x32_bf16 v[108:111], v[140:143], v[192:195], v[108:111]
	v_mfma_f32_16x16x32_bf16 v[96:99], v[132:135], v[200:203], v[96:99]
	v_mfma_f32_16x16x32_bf16 v[92:95], v[140:143], v[200:203], v[92:95]
	v_mfma_f32_16x16x32_bf16 v[80:83], v[132:135], v[208:211], v[80:83]
	v_mfma_f32_16x16x32_bf16 v[76:79], v[140:143], v[208:211], v[76:79]
	v_mfma_f32_16x16x32_bf16 v[128:131], v[136:139], v[188:191], v[128:131]
	v_mfma_f32_16x16x32_bf16 v[124:127], v[144:147], v[188:191], v[124:127]
	v_mfma_f32_16x16x32_bf16 v[112:115], v[136:139], v[196:199], v[112:115]
	v_mfma_f32_16x16x32_bf16 v[108:111], v[144:147], v[196:199], v[108:111]
	v_mfma_f32_16x16x32_bf16 v[96:99], v[136:139], v[204:207], v[96:99]
	v_mfma_f32_16x16x32_bf16 v[92:95], v[144:147], v[204:207], v[92:95]
	v_mfma_f32_16x16x32_bf16 v[80:83], v[136:139], v[212:215], v[80:83]
	v_mfma_f32_16x16x32_bf16 v[76:79], v[144:147], v[212:215], v[76:79]
	v_mfma_f32_16x16x32_bf16 v[120:123], v[148:151], v[164:167], v[120:123]
	v_mfma_f32_16x16x32_bf16 v[116:119], v[156:159], v[164:167], v[116:119]
	v_mfma_f32_16x16x32_bf16 v[104:107], v[148:151], v[192:195], v[104:107]
	v_mfma_f32_16x16x32_bf16 v[100:103], v[156:159], v[192:195], v[100:103]
	v_mfma_f32_16x16x32_bf16 v[88:91], v[148:151], v[200:203], v[88:91]
	v_mfma_f32_16x16x32_bf16 v[84:87], v[156:159], v[200:203], v[84:87]
	v_mfma_f32_16x16x32_bf16 v[72:75], v[148:151], v[208:211], v[72:75]
	v_mfma_f32_16x16x32_bf16 v[68:71], v[156:159], v[208:211], v[68:71]
	v_mfma_f32_16x16x32_bf16 v[120:123], v[152:155], v[188:191], v[120:123]
	v_mfma_f32_16x16x32_bf16 v[116:119], v[160:163], v[188:191], v[116:119]
	v_mfma_f32_16x16x32_bf16 v[104:107], v[152:155], v[196:199], v[104:107]
	v_mfma_f32_16x16x32_bf16 v[100:103], v[160:163], v[196:199], v[100:103]
	v_mfma_f32_16x16x32_bf16 v[88:91], v[152:155], v[204:207], v[88:91]
	v_mfma_f32_16x16x32_bf16 v[84:87], v[160:163], v[204:207], v[84:87]
	v_mfma_f32_16x16x32_bf16 v[72:75], v[152:155], v[212:215], v[72:75]
	v_mfma_f32_16x16x32_bf16 v[68:71], v[160:163], v[212:215], v[68:71]
	s_barrier

	s_add_i32 s11, s11, s74
	s_mov_b32 m0, s11
	ds_read_b128 v[164:167], v246 offset:49152
	ds_read_b128 v[188:191], v246 offset:50176
	ds_read_b128 v[192:195], v246 offset:51200
	ds_read_b128 v[196:199], v246 offset:52224
	ds_read_b128 v[200:203], v246 offset:53248
	ds_read_b128 v[204:207], v246 offset:54272
	ds_read_b128 v[208:211], v246 offset:55296
	ds_read_b128 v[212:215], v246 offset:56320
	s_add_u32 s100, s28, s24
	s_addc_u32 s101, s29, s25
	global_load_lds_dwordx4 v2, s[100:101]
	s_add_i32 m0, s11, 0x2000
	s_add_u32 s16, s28, 0x20080
	s_addc_u32 s17, s29, 0
	s_add_i32 s11, s94, s74
	global_load_lds_dwordx4 v168, s[100:101]
	s_mov_b32 m0, s11
	s_nop 0
	global_load_lds_dwordx4 v2, s[16:17]
	s_add_i32 m0, s11, 0x2000
	s_nop 0
	global_load_lds_dwordx4 v168, s[16:17]
	s_mov_b32 m0, s96
	s_nop 0
	s_add_u32 s100, s72, s24
	s_addc_u32 s101, s73, s25
	global_load_lds_dwordx4 v172, s[100:101]
	s_mov_b32 m0, s3
	s_nop 0
	global_load_lds_dwordx4 v170, s[100:101]
	s_waitcnt vmcnt(8)
	s_waitcnt lgkmcnt(0)

	s_barrier
	v_mfma_f32_16x16x32_bf16 v[64:67], v[132:135], v[164:167], v[64:67]
	v_mfma_f32_16x16x32_bf16 v[60:63], v[140:143], v[164:167], v[60:63]
	v_mfma_f32_16x16x32_bf16 v[48:51], v[132:135], v[192:195], v[48:51]
	v_mfma_f32_16x16x32_bf16 v[44:47], v[140:143], v[192:195], v[44:47]
	v_mfma_f32_16x16x32_bf16 v[32:35], v[132:135], v[200:203], v[32:35]
	v_mfma_f32_16x16x32_bf16 v[28:31], v[140:143], v[200:203], v[28:31]
	v_mfma_f32_16x16x32_bf16 v[16:19], v[132:135], v[208:211], v[16:19]
	v_mfma_f32_16x16x32_bf16 v[12:15], v[140:143], v[208:211], v[12:15]
	v_mfma_f32_16x16x32_bf16 v[64:67], v[136:139], v[188:191], v[64:67]
	v_mfma_f32_16x16x32_bf16 v[60:63], v[144:147], v[188:191], v[60:63]
	v_mfma_f32_16x16x32_bf16 v[48:51], v[136:139], v[196:199], v[48:51]
	v_mfma_f32_16x16x32_bf16 v[44:47], v[144:147], v[196:199], v[44:47]
	v_mfma_f32_16x16x32_bf16 v[32:35], v[136:139], v[204:207], v[32:35]
	v_mfma_f32_16x16x32_bf16 v[28:31], v[144:147], v[204:207], v[28:31]
	v_mfma_f32_16x16x32_bf16 v[16:19], v[136:139], v[212:215], v[16:19]
	v_mfma_f32_16x16x32_bf16 v[12:15], v[144:147], v[212:215], v[12:15]
	v_mfma_f32_16x16x32_bf16 v[56:59], v[148:151], v[164:167], v[56:59]
	v_mfma_f32_16x16x32_bf16 v[52:55], v[156:159], v[164:167], v[52:55]
	v_mfma_f32_16x16x32_bf16 v[40:43], v[148:151], v[192:195], v[40:43]
	v_mfma_f32_16x16x32_bf16 v[36:39], v[156:159], v[192:195], v[36:39]
	v_mfma_f32_16x16x32_bf16 v[24:27], v[148:151], v[200:203], v[24:27]
	v_mfma_f32_16x16x32_bf16 v[20:23], v[156:159], v[200:203], v[20:23]
	v_mfma_f32_16x16x32_bf16 v[8:11], v[148:151], v[208:211], v[8:11]
	v_mfma_f32_16x16x32_bf16 v[4:7], v[156:159], v[208:211], v[4:7]
	v_mfma_f32_16x16x32_bf16 v[56:59], v[152:155], v[188:191], v[56:59]
	v_mfma_f32_16x16x32_bf16 v[52:55], v[160:163], v[188:191], v[52:55]
	v_mfma_f32_16x16x32_bf16 v[40:43], v[152:155], v[196:199], v[40:43]
	v_mfma_f32_16x16x32_bf16 v[36:39], v[160:163], v[196:199], v[36:39]
	v_mfma_f32_16x16x32_bf16 v[24:27], v[152:155], v[204:207], v[24:27]
	v_mfma_f32_16x16x32_bf16 v[20:23], v[160:163], v[204:207], v[20:23]
	v_mfma_f32_16x16x32_bf16 v[8:11], v[152:155], v[212:215], v[8:11]
	v_mfma_f32_16x16x32_bf16 v[4:7], v[160:163], v[212:215], v[4:7]
	s_barrier

	s_add_i32 s10, s10, 2
	s_add_u32 vcc_lo, vcc_lo, 0x100
	s_addc_u32 vcc_hi, vcc_hi, 0
	s_add_u32 s48, s48, 0x100
	s_addc_u32 s49, s49, 0
	s_cmp_gt_u32 s10, 29
	s_cbranch_scc0 .LBB0_790
	s_setprio 0
	v_readlane_b32 s10, v252, 2
	v_readlane_b32 s11, v252, 3

.Lsp_870:
.LBB0_870:
	s_add_u32 s16, s44, 0xfff80080
	s_addc_u32 s17, s45, -1
	s_add_i32 s94, 0, 0x10000
	s_cmp_eq_u32 vcc_lo, 28
	s_cselect_b32 s47, s37, s17
	s_cselect_b32 s46, s88, s16
	s_cselect_b32 s29, s27, s96
	s_cselect_b32 s28, s89, s91
	s_add_i32 s95, 0, 0x14000
	v_add_u32_e32 v144, s94, v227
	v_add_u32_e32 v170, s95, v227
	ds_read_b128 v[132:135], v144
	ds_read_b128 v[136:139], v144 offset:1024
	ds_read_b128 v[140:143], v144 offset:2048
	ds_read_b128 v[144:147], v144 offset:3072
	ds_read_b128 v[148:151], v170
	ds_read_b128 v[152:155], v170 offset:1024
	ds_read_b128 v[166:169], v170 offset:2048
	ds_read_b128 v[170:173], v170 offset:3072
	s_add_i32 m0, s48, 0xc000
	ds_read_b128 v[184:187], v229
	ds_read_b128 v[188:191], v229 offset:1024
	ds_read_b128 v[192:195], v229 offset:2048
	ds_read_b128 v[196:199], v229 offset:3072
	ds_read_b128 v[200:203], v229 offset:4096
	ds_read_b128 v[204:207], v229 offset:5120
	ds_read_b128 v[208:211], v229 offset:6144
	ds_read_b128 v[212:215], v229 offset:7168
	global_load_lds_dwordx4 v162, s[44:45]
	s_add_i32 m0, s48, 0xe000
	s_nop 0
	global_load_lds_dwordx4 v164, s[44:45]
	s_waitcnt vmcnt(8)
	s_waitcnt lgkmcnt(0)

	s_barrier
	v_mfma_f32_16x16x32_bf16 v[128:131], v[132:135], v[184:187], v[128:131]
	v_mfma_f32_16x16x32_bf16 v[124:127], v[140:143], v[184:187], v[124:127]
	v_mfma_f32_16x16x32_bf16 v[112:115], v[132:135], v[192:195], v[112:115]
	v_mfma_f32_16x16x32_bf16 v[108:111], v[140:143], v[192:195], v[108:111]
	v_mfma_f32_16x16x32_bf16 v[96:99], v[132:135], v[200:203], v[96:99]
	v_mfma_f32_16x16x32_bf16 v[92:95], v[140:143], v[200:203], v[92:95]
	v_mfma_f32_16x16x32_bf16 v[80:83], v[132:135], v[208:211], v[80:83]
	v_mfma_f32_16x16x32_bf16 v[76:79], v[140:143], v[208:211], v[76:79]
	v_mfma_f32_16x16x32_bf16 v[128:131], v[136:139], v[188:191], v[128:131]
	v_mfma_f32_16x16x32_bf16 v[124:127], v[144:147], v[188:191], v[124:127]
	v_mfma_f32_16x16x32_bf16 v[112:115], v[136:139], v[196:199], v[112:115]
	v_mfma_f32_16x16x32_bf16 v[108:111], v[144:147], v[196:199], v[108:111]
	v_mfma_f32_16x16x32_bf16 v[96:99], v[136:139], v[204:207], v[96:99]
	v_mfma_f32_16x16x32_bf16 v[92:95], v[144:147], v[204:207], v[92:95]
	v_mfma_f32_16x16x32_bf16 v[80:83], v[136:139], v[212:215], v[80:83]
	v_mfma_f32_16x16x32_bf16 v[76:79], v[144:147], v[212:215], v[76:79]
	v_mfma_f32_16x16x32_bf16 v[120:123], v[148:151], v[184:187], v[120:123]
	v_mfma_f32_16x16x32_bf16 v[116:119], v[166:169], v[184:187], v[116:119]
	v_mfma_f32_16x16x32_bf16 v[104:107], v[148:151], v[192:195], v[104:107]
	v_mfma_f32_16x16x32_bf16 v[100:103], v[166:169], v[192:195], v[100:103]
	v_mfma_f32_16x16x32_bf16 v[88:91], v[148:151], v[200:203], v[88:91]
	v_mfma_f32_16x16x32_bf16 v[84:87], v[166:169], v[200:203], v[84:87]
	v_mfma_f32_16x16x32_bf16 v[72:75], v[148:151], v[208:211], v[72:75]
	v_mfma_f32_16x16x32_bf16 v[68:71], v[166:169], v[208:211], v[68:71]
	v_mfma_f32_16x16x32_bf16 v[120:123], v[152:155], v[188:191], v[120:123]
	v_mfma_f32_16x16x32_bf16 v[116:119], v[170:173], v[188:191], v[116:119]
	v_mfma_f32_16x16x32_bf16 v[104:107], v[152:155], v[196:199], v[104:107]
	v_mfma_f32_16x16x32_bf16 v[100:103], v[170:173], v[196:199], v[100:103]
	v_mfma_f32_16x16x32_bf16 v[88:91], v[152:155], v[204:207], v[88:91]
	v_mfma_f32_16x16x32_bf16 v[84:87], v[170:173], v[204:207], v[84:87]
	v_mfma_f32_16x16x32_bf16 v[72:75], v[152:155], v[212:215], v[72:75]
	v_mfma_f32_16x16x32_bf16 v[68:71], v[170:173], v[212:215], v[68:71]
	s_barrier

	s_add_i32 s16, s94, s33
	s_mov_b32 m0, s16
	ds_read_b128 v[184:187], v229 offset:16384
	ds_read_b128 v[188:191], v229 offset:17408
	ds_read_b128 v[192:195], v229 offset:18432
	ds_read_b128 v[196:199], v229 offset:19456
	ds_read_b128 v[200:203], v229 offset:20480
	ds_read_b128 v[204:207], v229 offset:21504
	ds_read_b128 v[208:211], v229 offset:22528
	ds_read_b128 v[212:215], v229 offset:23552
	global_load_lds_dwordx4 v2, s[28:29]
	s_add_i32 m0, s16, 0x2000
	s_add_u32 s16, s28, 0x80000
	s_addc_u32 s17, s29, 0
	s_add_i32 s94, s95, s33
	global_load_lds_dwordx4 v156, s[28:29]
	s_mov_b32 m0, s94
	s_nop 0
	global_load_lds_dwordx4 v2, s[16:17]
	s_add_i32 m0, s94, 0x2000
	s_nop 0
	global_load_lds_dwordx4 v156, s[16:17]
	s_mov_b32 m0, s48
	s_nop 0
	global_load_lds_dwordx4 v160, s[46:47]
	s_mov_b32 m0, s49
	s_nop 0
	global_load_lds_dwordx4 v158, s[46:47]
	s_waitcnt vmcnt(8)
	s_waitcnt lgkmcnt(0)

	s_barrier
	v_mfma_f32_16x16x32_bf16 v[64:67], v[132:135], v[184:187], v[64:67]
	v_mfma_f32_16x16x32_bf16 v[60:63], v[140:143], v[184:187], v[60:63]
	v_mfma_f32_16x16x32_bf16 v[48:51], v[132:135], v[192:195], v[48:51]
	v_mfma_f32_16x16x32_bf16 v[44:47], v[140:143], v[192:195], v[44:47]
	v_mfma_f32_16x16x32_bf16 v[32:35], v[132:135], v[200:203], v[32:35]
	v_mfma_f32_16x16x32_bf16 v[28:31], v[140:143], v[200:203], v[28:31]
	v_mfma_f32_16x16x32_bf16 v[16:19], v[132:135], v[208:211], v[16:19]
	v_mfma_f32_16x16x32_bf16 v[12:15], v[140:143], v[208:211], v[12:15]
	v_mfma_f32_16x16x32_bf16 v[64:67], v[136:139], v[188:191], v[64:67]
	v_mfma_f32_16x16x32_bf16 v[60:63], v[144:147], v[188:191], v[60:63]
	v_mfma_f32_16x16x32_bf16 v[48:51], v[136:139], v[196:199], v[48:51]
	v_mfma_f32_16x16x32_bf16 v[44:47], v[144:147], v[196:199], v[44:47]
	v_mfma_f32_16x16x32_bf16 v[32:35], v[136:139], v[204:207], v[32:35]
	v_mfma_f32_16x16x32_bf16 v[28:31], v[144:147], v[204:207], v[28:31]
	v_mfma_f32_16x16x32_bf16 v[16:19], v[136:139], v[212:215], v[16:19]
	v_mfma_f32_16x16x32_bf16 v[12:15], v[144:147], v[212:215], v[12:15]
	v_mfma_f32_16x16x32_bf16 v[56:59], v[148:151], v[184:187], v[56:59]
	v_mfma_f32_16x16x32_bf16 v[52:55], v[166:169], v[184:187], v[52:55]
	v_mfma_f32_16x16x32_bf16 v[40:43], v[148:151], v[192:195], v[40:43]
	v_mfma_f32_16x16x32_bf16 v[36:39], v[166:169], v[192:195], v[36:39]
	v_mfma_f32_16x16x32_bf16 v[24:27], v[148:151], v[200:203], v[24:27]
	v_mfma_f32_16x16x32_bf16 v[20:23], v[166:169], v[200:203], v[20:23]
	v_mfma_f32_16x16x32_bf16 v[8:11], v[148:151], v[208:211], v[8:11]
	v_mfma_f32_16x16x32_bf16 v[4:7], v[166:169], v[208:211], v[4:7]
	v_mfma_f32_16x16x32_bf16 v[56:59], v[152:155], v[188:191], v[56:59]
	v_mfma_f32_16x16x32_bf16 v[52:55], v[170:173], v[188:191], v[52:55]
	v_mfma_f32_16x16x32_bf16 v[40:43], v[152:155], v[196:199], v[40:43]
	v_mfma_f32_16x16x32_bf16 v[36:39], v[170:173], v[196:199], v[36:39]
	v_mfma_f32_16x16x32_bf16 v[24:27], v[152:155], v[204:207], v[24:27]
	v_mfma_f32_16x16x32_bf16 v[20:23], v[170:173], v[204:207], v[20:23]
	v_mfma_f32_16x16x32_bf16 v[8:11], v[152:155], v[212:215], v[8:11]
	v_mfma_f32_16x16x32_bf16 v[4:7], v[170:173], v[212:215], v[4:7]
	s_barrier

	s_add_i32 s94, 0, 0x18000
	s_add_i32 s95, 0, 0x1c000
	v_add_u32_e32 v144, s94, v227
	v_add_u32_e32 v170, s95, v227
	ds_read_b128 v[132:135], v144
	ds_read_b128 v[136:139], v144 offset:1024
	ds_read_b128 v[140:143], v144 offset:2048
	ds_read_b128 v[144:147], v144 offset:3072
	ds_read_b128 v[148:151], v170
	ds_read_b128 v[152:155], v170 offset:1024
	ds_read_b128 v[166:169], v170 offset:2048
	ds_read_b128 v[170:173], v170 offset:3072
	s_add_u32 s16, s46, 0x80000
	s_addc_u32 s17, s47, 0
	s_mov_b32 m0, s50
	ds_read_b128 v[184:187], v229 offset:32768
	ds_read_b128 v[188:191], v229 offset:33792
	ds_read_b128 v[192:195], v229 offset:34816
	ds_read_b128 v[196:199], v229 offset:35840
	ds_read_b128 v[200:203], v229 offset:36864
	ds_read_b128 v[204:207], v229 offset:37888
	ds_read_b128 v[208:211], v229 offset:38912
	ds_read_b128 v[212:215], v229 offset:39936
	global_load_lds_dwordx4 v160, s[16:17]
	s_mov_b32 m0, s51
	s_nop 0
	global_load_lds_dwordx4 v158, s[16:17]
	s_waitcnt vmcnt(8)
	s_waitcnt lgkmcnt(0)

	s_barrier
	v_mfma_f32_16x16x32_bf16 v[128:131], v[132:135], v[184:187], v[128:131]
	v_mfma_f32_16x16x32_bf16 v[124:127], v[140:143], v[184:187], v[124:127]
	v_mfma_f32_16x16x32_bf16 v[112:115], v[132:135], v[192:195], v[112:115]
	v_mfma_f32_16x16x32_bf16 v[108:111], v[140:143], v[192:195], v[108:111]
	v_mfma_f32_16x16x32_bf16 v[96:99], v[132:135], v[200:203], v[96:99]
	v_mfma_f32_16x16x32_bf16 v[92:95], v[140:143], v[200:203], v[92:95]
	v_mfma_f32_16x16x32_bf16 v[80:83], v[132:135], v[208:211], v[80:83]
	v_mfma_f32_16x16x32_bf16 v[76:79], v[140:143], v[208:211], v[76:79]
	v_mfma_f32_16x16x32_bf16 v[128:131], v[136:139], v[188:191], v[128:131]
	v_mfma_f32_16x16x32_bf16 v[124:127], v[144:147], v[188:191], v[124:127]
	v_mfma_f32_16x16x32_bf16 v[112:115], v[136:139], v[196:199], v[112:115]
	v_mfma_f32_16x16x32_bf16 v[108:111], v[144:147], v[196:199], v[108:111]
	v_mfma_f32_16x16x32_bf16 v[96:99], v[136:139], v[204:207], v[96:99]
	v_mfma_f32_16x16x32_bf16 v[92:95], v[144:147], v[204:207], v[92:95]
	v_mfma_f32_16x16x32_bf16 v[80:83], v[136:139], v[212:215], v[80:83]
	v_mfma_f32_16x16x32_bf16 v[76:79], v[144:147], v[212:215], v[76:79]
	v_mfma_f32_16x16x32_bf16 v[120:123], v[148:151], v[184:187], v[120:123]
	v_mfma_f32_16x16x32_bf16 v[116:119], v[166:169], v[184:187], v[116:119]
	v_mfma_f32_16x16x32_bf16 v[104:107], v[148:151], v[192:195], v[104:107]
	v_mfma_f32_16x16x32_bf16 v[100:103], v[166:169], v[192:195], v[100:103]
	v_mfma_f32_16x16x32_bf16 v[88:91], v[148:151], v[200:203], v[88:91]
	v_mfma_f32_16x16x32_bf16 v[84:87], v[166:169], v[200:203], v[84:87]
	v_mfma_f32_16x16x32_bf16 v[72:75], v[148:151], v[208:211], v[72:75]
	v_mfma_f32_16x16x32_bf16 v[68:71], v[166:169], v[208:211], v[68:71]
	v_mfma_f32_16x16x32_bf16 v[120:123], v[152:155], v[188:191], v[120:123]
	v_mfma_f32_16x16x32_bf16 v[116:119], v[170:173], v[188:191], v[116:119]
	v_mfma_f32_16x16x32_bf16 v[104:107], v[152:155], v[196:199], v[104:107]
	v_mfma_f32_16x16x32_bf16 v[100:103], v[170:173], v[196:199], v[100:103]
	v_mfma_f32_16x16x32_bf16 v[88:91], v[152:155], v[204:207], v[88:91]
	v_mfma_f32_16x16x32_bf16 v[84:87], v[170:173], v[204:207], v[84:87]
	v_mfma_f32_16x16x32_bf16 v[72:75], v[152:155], v[212:215], v[72:75]
	v_mfma_f32_16x16x32_bf16 v[68:71], v[170:173], v[212:215], v[68:71]
	s_barrier

	s_add_i32 s16, s94, s33
	s_mov_b32 m0, s16
	ds_read_b128 v[184:187], v229 offset:49152
	ds_read_b128 v[188:191], v229 offset:50176
	ds_read_b128 v[192:195], v229 offset:51200
	ds_read_b128 v[196:199], v229 offset:52224
	ds_read_b128 v[200:203], v229 offset:53248
	ds_read_b128 v[204:207], v229 offset:54272
	ds_read_b128 v[208:211], v229 offset:55296
	ds_read_b128 v[212:215], v229 offset:56320
	s_add_u32 s100, s28, s24
	s_addc_u32 s101, s29, s25
	global_load_lds_dwordx4 v2, s[100:101]
	s_add_i32 m0, s16, 0x2000
	s_add_u32 s16, s28, 0x80080
	s_addc_u32 s17, s29, 0
	s_add_i32 s28, s95, s33
	global_load_lds_dwordx4 v156, s[100:101]
	s_mov_b32 m0, s28
	s_nop 0
	global_load_lds_dwordx4 v2, s[16:17]
	s_add_i32 m0, s28, 0x2000
	s_nop 0
	global_load_lds_dwordx4 v156, s[16:17]
	s_mov_b32 m0, s72
	s_nop 0
	s_add_u32 s100, s46, s24
	s_addc_u32 s101, s47, s25
	global_load_lds_dwordx4 v160, s[100:101]
	s_mov_b32 m0, s73
	s_nop 0
	global_load_lds_dwordx4 v158, s[100:101]
	s_waitcnt vmcnt(8)
	s_waitcnt lgkmcnt(0)

	s_barrier
	v_mfma_f32_16x16x32_bf16 v[64:67], v[132:135], v[184:187], v[64:67]
	v_mfma_f32_16x16x32_bf16 v[60:63], v[140:143], v[184:187], v[60:63]
	v_mfma_f32_16x16x32_bf16 v[48:51], v[132:135], v[192:195], v[48:51]
	v_mfma_f32_16x16x32_bf16 v[44:47], v[140:143], v[192:195], v[44:47]
	v_mfma_f32_16x16x32_bf16 v[32:35], v[132:135], v[200:203], v[32:35]
	v_mfma_f32_16x16x32_bf16 v[28:31], v[140:143], v[200:203], v[28:31]
	v_mfma_f32_16x16x32_bf16 v[16:19], v[132:135], v[208:211], v[16:19]
	v_mfma_f32_16x16x32_bf16 v[12:15], v[140:143], v[208:211], v[12:15]
	v_mfma_f32_16x16x32_bf16 v[64:67], v[136:139], v[188:191], v[64:67]
	v_mfma_f32_16x16x32_bf16 v[60:63], v[144:147], v[188:191], v[60:63]
	v_mfma_f32_16x16x32_bf16 v[48:51], v[136:139], v[196:199], v[48:51]
	v_mfma_f32_16x16x32_bf16 v[44:47], v[144:147], v[196:199], v[44:47]
	v_mfma_f32_16x16x32_bf16 v[32:35], v[136:139], v[204:207], v[32:35]
	v_mfma_f32_16x16x32_bf16 v[28:31], v[144:147], v[204:207], v[28:31]
	v_mfma_f32_16x16x32_bf16 v[16:19], v[136:139], v[212:215], v[16:19]
	v_mfma_f32_16x16x32_bf16 v[12:15], v[144:147], v[212:215], v[12:15]
	v_mfma_f32_16x16x32_bf16 v[56:59], v[148:151], v[184:187], v[56:59]
	v_mfma_f32_16x16x32_bf16 v[52:55], v[166:169], v[184:187], v[52:55]
	v_mfma_f32_16x16x32_bf16 v[40:43], v[148:151], v[192:195], v[40:43]
	v_mfma_f32_16x16x32_bf16 v[36:39], v[166:169], v[192:195], v[36:39]
	v_mfma_f32_16x16x32_bf16 v[24:27], v[148:151], v[200:203], v[24:27]
	v_mfma_f32_16x16x32_bf16 v[20:23], v[166:169], v[200:203], v[20:23]
	v_mfma_f32_16x16x32_bf16 v[8:11], v[148:151], v[208:211], v[8:11]
	v_mfma_f32_16x16x32_bf16 v[4:7], v[166:169], v[208:211], v[4:7]
	v_mfma_f32_16x16x32_bf16 v[56:59], v[152:155], v[188:191], v[56:59]
	v_mfma_f32_16x16x32_bf16 v[52:55], v[170:173], v[188:191], v[52:55]
	v_mfma_f32_16x16x32_bf16 v[40:43], v[152:155], v[196:199], v[40:43]
	v_mfma_f32_16x16x32_bf16 v[36:39], v[170:173], v[196:199], v[36:39]
	v_mfma_f32_16x16x32_bf16 v[24:27], v[152:155], v[204:207], v[24:27]
	v_mfma_f32_16x16x32_bf16 v[20:23], v[170:173], v[204:207], v[20:23]
	v_mfma_f32_16x16x32_bf16 v[8:11], v[152:155], v[212:215], v[8:11]
	v_mfma_f32_16x16x32_bf16 v[4:7], v[170:173], v[212:215], v[4:7]
	s_barrier

	s_add_i32 vcc_lo, vcc_lo, 2
	s_add_u32 s44, s44, 0x100
	s_addc_u32 s45, s45, 0
	s_add_u32 s91, s91, 0x100
	s_addc_u32 s96, s96, 0
	s_cmp_gt_u32 vcc_lo, 29
	s_cbranch_scc0 .LBB0_870
	s_setprio 0

.Lsp_1035:
.LBB0_1035:
	s_add_u32 s46, s50, 0x100
	s_addc_u32 s47, s51, 0
	s_add_i32 s16, 0, 0x10000
	s_cmpk_eq_i32 s48, 0x54
	s_cselect_b32 s73, s23, s47
	s_cselect_b32 s72, s22, s46
	s_cselect_b32 s29, s27, vcc_hi
	s_cselect_b32 s28, s26, vcc_lo
	s_add_i32 s49, 0, 0x14000
	v_add_u32_e32 v144, s16, v244
	v_add_u32_e32 v160, s49, v244
	ds_read_b128 v[132:135], v144
	ds_read_b128 v[136:139], v144 offset:1024
	ds_read_b128 v[140:143], v144 offset:2048
	ds_read_b128 v[144:147], v144 offset:3072
	ds_read_b128 v[148:151], v160
	ds_read_b128 v[152:155], v160 offset:1024
	ds_read_b128 v[156:159], v160 offset:2048
	ds_read_b128 v[160:163], v160 offset:3072
	s_add_i32 m0, s77, 0xc000
	ds_read_b128 v[164:167], v246
	ds_read_b128 v[188:191], v246 offset:1024
	ds_read_b128 v[192:195], v246 offset:2048
	ds_read_b128 v[196:199], v246 offset:3072
	ds_read_b128 v[200:203], v246 offset:4096
	ds_read_b128 v[204:207], v246 offset:5120
	ds_read_b128 v[208:211], v246 offset:6144
	ds_read_b128 v[212:215], v246 offset:7168
	global_load_lds_dwordx4 v184, s[50:51]
	s_add_i32 m0, s77, 0xe000
	s_nop 0
	global_load_lds_dwordx4 v186, s[50:51]
	s_waitcnt vmcnt(8)
	s_waitcnt lgkmcnt(0)

	s_barrier
	v_mfma_f32_16x16x32_bf16 v[128:131], v[132:135], v[164:167], v[128:131]
	v_mfma_f32_16x16x32_bf16 v[124:127], v[140:143], v[164:167], v[124:127]
	v_mfma_f32_16x16x32_bf16 v[112:115], v[132:135], v[192:195], v[112:115]
	v_mfma_f32_16x16x32_bf16 v[108:111], v[140:143], v[192:195], v[108:111]
	v_mfma_f32_16x16x32_bf16 v[96:99], v[132:135], v[200:203], v[96:99]
	v_mfma_f32_16x16x32_bf16 v[92:95], v[140:143], v[200:203], v[92:95]
	v_mfma_f32_16x16x32_bf16 v[80:83], v[132:135], v[208:211], v[80:83]
	v_mfma_f32_16x16x32_bf16 v[76:79], v[140:143], v[208:211], v[76:79]
	v_mfma_f32_16x16x32_bf16 v[128:131], v[136:139], v[188:191], v[128:131]
	v_mfma_f32_16x16x32_bf16 v[124:127], v[144:147], v[188:191], v[124:127]
	v_mfma_f32_16x16x32_bf16 v[112:115], v[136:139], v[196:199], v[112:115]
	v_mfma_f32_16x16x32_bf16 v[108:111], v[144:147], v[196:199], v[108:111]
	v_mfma_f32_16x16x32_bf16 v[96:99], v[136:139], v[204:207], v[96:99]
	v_mfma_f32_16x16x32_bf16 v[92:95], v[144:147], v[204:207], v[92:95]
	v_mfma_f32_16x16x32_bf16 v[80:83], v[136:139], v[212:215], v[80:83]
	v_mfma_f32_16x16x32_bf16 v[76:79], v[144:147], v[212:215], v[76:79]
	v_mfma_f32_16x16x32_bf16 v[120:123], v[148:151], v[164:167], v[120:123]
	v_mfma_f32_16x16x32_bf16 v[116:119], v[156:159], v[164:167], v[116:119]
	v_mfma_f32_16x16x32_bf16 v[104:107], v[148:151], v[192:195], v[104:107]
	v_mfma_f32_16x16x32_bf16 v[100:103], v[156:159], v[192:195], v[100:103]
	v_mfma_f32_16x16x32_bf16 v[88:91], v[148:151], v[200:203], v[88:91]
	v_mfma_f32_16x16x32_bf16 v[84:87], v[156:159], v[200:203], v[84:87]
	v_mfma_f32_16x16x32_bf16 v[72:75], v[148:151], v[208:211], v[72:75]
	v_mfma_f32_16x16x32_bf16 v[68:71], v[156:159], v[208:211], v[68:71]
	v_mfma_f32_16x16x32_bf16 v[120:123], v[152:155], v[188:191], v[120:123]
	v_mfma_f32_16x16x32_bf16 v[116:119], v[160:163], v[188:191], v[116:119]
	v_mfma_f32_16x16x32_bf16 v[104:107], v[152:155], v[196:199], v[104:107]
	v_mfma_f32_16x16x32_bf16 v[100:103], v[160:163], v[196:199], v[100:103]
	v_mfma_f32_16x16x32_bf16 v[88:91], v[152:155], v[204:207], v[88:91]
	v_mfma_f32_16x16x32_bf16 v[84:87], v[160:163], v[204:207], v[84:87]
	v_mfma_f32_16x16x32_bf16 v[72:75], v[152:155], v[212:215], v[72:75]
	v_mfma_f32_16x16x32_bf16 v[68:71], v[160:163], v[212:215], v[68:71]
	s_barrier

	s_add_i32 s16, s16, s74
	s_mov_b32 m0, s16
	ds_read_b128 v[164:167], v246 offset:16384
	ds_read_b128 v[188:191], v246 offset:17408
	ds_read_b128 v[192:195], v246 offset:18432
	ds_read_b128 v[196:199], v246 offset:19456
	ds_read_b128 v[200:203], v246 offset:20480
	ds_read_b128 v[204:207], v246 offset:21504
	ds_read_b128 v[208:211], v246 offset:22528
	ds_read_b128 v[212:215], v246 offset:23552
	global_load_lds_dwordx4 v2, s[28:29]
	s_add_i32 m0, s16, 0x2000
	s_add_u32 s16, s28, 0x58000
	s_addc_u32 s17, s29, 0
	s_add_i32 s49, s49, s74
	global_load_lds_dwordx4 v168, s[28:29]
	s_mov_b32 m0, s49
	s_nop 0
	global_load_lds_dwordx4 v2, s[16:17]
	s_add_i32 m0, s49, 0x2000
	s_nop 0
	global_load_lds_dwordx4 v168, s[16:17]
	s_mov_b32 m0, s77
	s_nop 0
	global_load_lds_dwordx4 v172, s[72:73]
	s_mov_b32 m0, s78
	s_nop 0
	global_load_lds_dwordx4 v170, s[72:73]
	s_waitcnt vmcnt(8)
	s_waitcnt lgkmcnt(0)

	s_barrier
	v_mfma_f32_16x16x32_bf16 v[64:67], v[132:135], v[164:167], v[64:67]
	v_mfma_f32_16x16x32_bf16 v[60:63], v[140:143], v[164:167], v[60:63]
	v_mfma_f32_16x16x32_bf16 v[48:51], v[132:135], v[192:195], v[48:51]
	v_mfma_f32_16x16x32_bf16 v[44:47], v[140:143], v[192:195], v[44:47]
	v_mfma_f32_16x16x32_bf16 v[32:35], v[132:135], v[200:203], v[32:35]
	v_mfma_f32_16x16x32_bf16 v[28:31], v[140:143], v[200:203], v[28:31]
	v_mfma_f32_16x16x32_bf16 v[16:19], v[132:135], v[208:211], v[16:19]
	v_mfma_f32_16x16x32_bf16 v[12:15], v[140:143], v[208:211], v[12:15]
	v_mfma_f32_16x16x32_bf16 v[64:67], v[136:139], v[188:191], v[64:67]
	v_mfma_f32_16x16x32_bf16 v[60:63], v[144:147], v[188:191], v[60:63]
	v_mfma_f32_16x16x32_bf16 v[48:51], v[136:139], v[196:199], v[48:51]
	v_mfma_f32_16x16x32_bf16 v[44:47], v[144:147], v[196:199], v[44:47]
	v_mfma_f32_16x16x32_bf16 v[32:35], v[136:139], v[204:207], v[32:35]
	v_mfma_f32_16x16x32_bf16 v[28:31], v[144:147], v[204:207], v[28:31]
	v_mfma_f32_16x16x32_bf16 v[16:19], v[136:139], v[212:215], v[16:19]
	v_mfma_f32_16x16x32_bf16 v[12:15], v[144:147], v[212:215], v[12:15]
	v_mfma_f32_16x16x32_bf16 v[56:59], v[148:151], v[164:167], v[56:59]
	v_mfma_f32_16x16x32_bf16 v[52:55], v[156:159], v[164:167], v[52:55]
	v_mfma_f32_16x16x32_bf16 v[40:43], v[148:151], v[192:195], v[40:43]
	v_mfma_f32_16x16x32_bf16 v[36:39], v[156:159], v[192:195], v[36:39]
	v_mfma_f32_16x16x32_bf16 v[24:27], v[148:151], v[200:203], v[24:27]
	v_mfma_f32_16x16x32_bf16 v[20:23], v[156:159], v[200:203], v[20:23]
	v_mfma_f32_16x16x32_bf16 v[8:11], v[148:151], v[208:211], v[8:11]
	v_mfma_f32_16x16x32_bf16 v[4:7], v[156:159], v[208:211], v[4:7]
	v_mfma_f32_16x16x32_bf16 v[56:59], v[152:155], v[188:191], v[56:59]
	v_mfma_f32_16x16x32_bf16 v[52:55], v[160:163], v[188:191], v[52:55]
	v_mfma_f32_16x16x32_bf16 v[40:43], v[152:155], v[196:199], v[40:43]
	v_mfma_f32_16x16x32_bf16 v[36:39], v[160:163], v[196:199], v[36:39]
	v_mfma_f32_16x16x32_bf16 v[24:27], v[152:155], v[204:207], v[24:27]
	v_mfma_f32_16x16x32_bf16 v[20:23], v[160:163], v[204:207], v[20:23]
	v_mfma_f32_16x16x32_bf16 v[8:11], v[152:155], v[212:215], v[8:11]
	v_mfma_f32_16x16x32_bf16 v[4:7], v[160:163], v[212:215], v[4:7]
	s_barrier

	s_add_i32 s49, 0, 0x18000
	s_add_i32 s50, 0, 0x1c000
	v_add_u32_e32 v144, s49, v244
	v_add_u32_e32 v160, s50, v244
	ds_read_b128 v[132:135], v144
	ds_read_b128 v[136:139], v144 offset:1024
	ds_read_b128 v[140:143], v144 offset:2048
	ds_read_b128 v[144:147], v144 offset:3072
	ds_read_b128 v[148:151], v160
	ds_read_b128 v[152:155], v160 offset:1024
	ds_read_b128 v[156:159], v160 offset:2048
	ds_read_b128 v[160:163], v160 offset:3072
	s_add_u32 s16, s72, 0x160000
	s_addc_u32 s17, s73, 0
	s_mov_b32 m0, s18
	ds_read_b128 v[164:167], v246 offset:32768
	ds_read_b128 v[188:191], v246 offset:33792
	ds_read_b128 v[192:195], v246 offset:34816
	ds_read_b128 v[196:199], v246 offset:35840
	ds_read_b128 v[200:203], v246 offset:36864
	ds_read_b128 v[204:207], v246 offset:37888
	ds_read_b128 v[208:211], v246 offset:38912
	ds_read_b128 v[212:215], v246 offset:39936
	global_load_lds_dwordx4 v172, s[16:17]
	s_mov_b32 m0, s19
	s_nop 0
	global_load_lds_dwordx4 v170, s[16:17]
	s_waitcnt vmcnt(8)
	s_waitcnt lgkmcnt(0)

	s_barrier
	v_mfma_f32_16x16x32_bf16 v[128:131], v[132:135], v[164:167], v[128:131]
	v_mfma_f32_16x16x32_bf16 v[124:127], v[140:143], v[164:167], v[124:127]
	v_mfma_f32_16x16x32_bf16 v[112:115], v[132:135], v[192:195], v[112:115]
	v_mfma_f32_16x16x32_bf16 v[108:111], v[140:143], v[192:195], v[108:111]
	v_mfma_f32_16x16x32_bf16 v[96:99], v[132:135], v[200:203], v[96:99]
	v_mfma_f32_16x16x32_bf16 v[92:95], v[140:143], v[200:203], v[92:95]
	v_mfma_f32_16x16x32_bf16 v[80:83], v[132:135], v[208:211], v[80:83]
	v_mfma_f32_16x16x32_bf16 v[76:79], v[140:143], v[208:211], v[76:79]
	v_mfma_f32_16x16x32_bf16 v[128:131], v[136:139], v[188:191], v[128:131]
	v_mfma_f32_16x16x32_bf16 v[124:127], v[144:147], v[188:191], v[124:127]
	v_mfma_f32_16x16x32_bf16 v[112:115], v[136:139], v[196:199], v[112:115]
	v_mfma_f32_16x16x32_bf16 v[108:111], v[144:147], v[196:199], v[108:111]
	v_mfma_f32_16x16x32_bf16 v[96:99], v[136:139], v[204:207], v[96:99]
	v_mfma_f32_16x16x32_bf16 v[92:95], v[144:147], v[204:207], v[92:95]
	v_mfma_f32_16x16x32_bf16 v[80:83], v[136:139], v[212:215], v[80:83]
	v_mfma_f32_16x16x32_bf16 v[76:79], v[144:147], v[212:215], v[76:79]
	v_mfma_f32_16x16x32_bf16 v[120:123], v[148:151], v[164:167], v[120:123]
	v_mfma_f32_16x16x32_bf16 v[116:119], v[156:159], v[164:167], v[116:119]
	v_mfma_f32_16x16x32_bf16 v[104:107], v[148:151], v[192:195], v[104:107]
	v_mfma_f32_16x16x32_bf16 v[100:103], v[156:159], v[192:195], v[100:103]
	v_mfma_f32_16x16x32_bf16 v[88:91], v[148:151], v[200:203], v[88:91]
	v_mfma_f32_16x16x32_bf16 v[84:87], v[156:159], v[200:203], v[84:87]
	v_mfma_f32_16x16x32_bf16 v[72:75], v[148:151], v[208:211], v[72:75]
	v_mfma_f32_16x16x32_bf16 v[68:71], v[156:159], v[208:211], v[68:71]
	v_mfma_f32_16x16x32_bf16 v[120:123], v[152:155], v[188:191], v[120:123]
	v_mfma_f32_16x16x32_bf16 v[116:119], v[160:163], v[188:191], v[116:119]
	v_mfma_f32_16x16x32_bf16 v[104:107], v[152:155], v[196:199], v[104:107]
	v_mfma_f32_16x16x32_bf16 v[100:103], v[160:163], v[196:199], v[100:103]
	v_mfma_f32_16x16x32_bf16 v[88:91], v[152:155], v[204:207], v[88:91]
	v_mfma_f32_16x16x32_bf16 v[84:87], v[160:163], v[204:207], v[84:87]
	v_mfma_f32_16x16x32_bf16 v[72:75], v[152:155], v[212:215], v[72:75]
	v_mfma_f32_16x16x32_bf16 v[68:71], v[160:163], v[212:215], v[68:71]
	s_barrier

	s_add_i32 s16, s49, s74
	s_mov_b32 m0, s16
	ds_read_b128 v[164:167], v246 offset:49152
	ds_read_b128 v[188:191], v246 offset:50176
	ds_read_b128 v[192:195], v246 offset:51200
	ds_read_b128 v[196:199], v246 offset:52224
	ds_read_b128 v[200:203], v246 offset:53248
	ds_read_b128 v[204:207], v246 offset:54272
	ds_read_b128 v[208:211], v246 offset:55296
	ds_read_b128 v[212:215], v246 offset:56320
	s_add_u32 s100, s28, s24
	s_addc_u32 s101, s29, s25
	global_load_lds_dwordx4 v2, s[100:101]
	s_add_i32 m0, s16, 0x2000
	s_add_u32 s16, s28, 0x58080
	s_addc_u32 s17, s29, 0
	s_add_i32 s28, s50, s74
	global_load_lds_dwordx4 v168, s[100:101]
	s_mov_b32 m0, s28
	s_nop 0
	global_load_lds_dwordx4 v2, s[16:17]
	s_add_i32 m0, s28, 0x2000
	s_nop 0
	global_load_lds_dwordx4 v168, s[16:17]
	s_mov_b32 m0, s96
	s_nop 0
	s_add_u32 s100, s72, s24
	s_addc_u32 s101, s73, s25
	global_load_lds_dwordx4 v172, s[100:101]
	s_mov_b32 m0, s3
	s_nop 0
	global_load_lds_dwordx4 v170, s[100:101]
	s_waitcnt vmcnt(8)
	s_waitcnt lgkmcnt(0)

	s_barrier
	v_mfma_f32_16x16x32_bf16 v[64:67], v[132:135], v[164:167], v[64:67]
	v_mfma_f32_16x16x32_bf16 v[60:63], v[140:143], v[164:167], v[60:63]
	v_mfma_f32_16x16x32_bf16 v[48:51], v[132:135], v[192:195], v[48:51]
	v_mfma_f32_16x16x32_bf16 v[44:47], v[140:143], v[192:195], v[44:47]
	v_mfma_f32_16x16x32_bf16 v[32:35], v[132:135], v[200:203], v[32:35]
	v_mfma_f32_16x16x32_bf16 v[28:31], v[140:143], v[200:203], v[28:31]
	v_mfma_f32_16x16x32_bf16 v[16:19], v[132:135], v[208:211], v[16:19]
	v_mfma_f32_16x16x32_bf16 v[12:15], v[140:143], v[208:211], v[12:15]
	v_mfma_f32_16x16x32_bf16 v[64:67], v[136:139], v[188:191], v[64:67]
	v_mfma_f32_16x16x32_bf16 v[60:63], v[144:147], v[188:191], v[60:63]
	v_mfma_f32_16x16x32_bf16 v[48:51], v[136:139], v[196:199], v[48:51]
	v_mfma_f32_16x16x32_bf16 v[44:47], v[144:147], v[196:199], v[44:47]
	v_mfma_f32_16x16x32_bf16 v[32:35], v[136:139], v[204:207], v[32:35]
	v_mfma_f32_16x16x32_bf16 v[28:31], v[144:147], v[204:207], v[28:31]
	v_mfma_f32_16x16x32_bf16 v[16:19], v[136:139], v[212:215], v[16:19]
	v_mfma_f32_16x16x32_bf16 v[12:15], v[144:147], v[212:215], v[12:15]
	v_mfma_f32_16x16x32_bf16 v[56:59], v[148:151], v[164:167], v[56:59]
	v_mfma_f32_16x16x32_bf16 v[52:55], v[156:159], v[164:167], v[52:55]
	v_mfma_f32_16x16x32_bf16 v[40:43], v[148:151], v[192:195], v[40:43]
	v_mfma_f32_16x16x32_bf16 v[36:39], v[156:159], v[192:195], v[36:39]
	v_mfma_f32_16x16x32_bf16 v[24:27], v[148:151], v[200:203], v[24:27]
	v_mfma_f32_16x16x32_bf16 v[20:23], v[156:159], v[200:203], v[20:23]
	v_mfma_f32_16x16x32_bf16 v[8:11], v[148:151], v[208:211], v[8:11]
	v_mfma_f32_16x16x32_bf16 v[4:7], v[156:159], v[208:211], v[4:7]
	v_mfma_f32_16x16x32_bf16 v[56:59], v[152:155], v[188:191], v[56:59]
	v_mfma_f32_16x16x32_bf16 v[52:55], v[160:163], v[188:191], v[52:55]
	v_mfma_f32_16x16x32_bf16 v[40:43], v[152:155], v[196:199], v[40:43]
	v_mfma_f32_16x16x32_bf16 v[36:39], v[160:163], v[196:199], v[36:39]
	v_mfma_f32_16x16x32_bf16 v[24:27], v[152:155], v[204:207], v[24:27]
	v_mfma_f32_16x16x32_bf16 v[20:23], v[160:163], v[204:207], v[20:23]
	v_mfma_f32_16x16x32_bf16 v[8:11], v[152:155], v[212:215], v[8:11]
	v_mfma_f32_16x16x32_bf16 v[4:7], v[160:163], v[212:215], v[4:7]
	s_barrier

	s_add_i32 s48, s48, 2
	s_add_u32 vcc_lo, vcc_lo, 0x100
	s_addc_u32 vcc_hi, vcc_hi, 0
	s_cmpk_gt_u32 s48, 0x55
	s_mov_b64 s[50:51], s[46:47]
	s_cbranch_scc0 .LBB0_1035
	s_setprio 0
	v_readlane_b32 s16, v252, 12
	v_readlane_b32 s17, v252, 13
